# K-loops: last ds_read of each read group fills the M0-write wait slot before the second LDS-DMA (s_nop dropped)
# baseline (speedup 1.0000x reference)
.Lpeel_p1:
	ds_read_b128 v[130:133], v173
	ds_read_b128 v[134:137], v173 offset:1024
	ds_read_b128 v[138:141], v173 offset:2048
	ds_read_b128 v[142:145], v173 offset:3072
	s_add_u32 s6, s2, 0xfffc0080
	s_addc_u32 s7, s3, -1
	s_cmp_eq_u32 s73, 12
	s_cselect_b32 s9, s1, s7
	s_cselect_b32 s8, s33, s6
	s_cselect_b32 s7, s39, s72
	s_cselect_b32 s6, s41, s71
	s_add_i32 m0, s50, 0xc000
	ds_read_b128 v[180:183], v175
	ds_read_b128 v[184:187], v175 offset:1024
	ds_read_b128 v[190:193], v175 offset:2048
	ds_read_b128 v[194:197], v175 offset:3072
	ds_read_b128 v[198:201], v175 offset:4096
	ds_read_b128 v[202:205], v175 offset:5120
	ds_read_b128 v[206:209], v175 offset:6144
	global_load_lds_dwordx4 v156, s[2:3]
	s_add_i32 m0, s50, 0xe000
	ds_read_b128 v[210:213], v175 offset:7168
	global_load_lds_dwordx4 v158, s[2:3]
	s_waitcnt lgkmcnt(8)
	s_barrier
	s_waitcnt lgkmcnt(0)
	v_mfma_f32_16x16x32_bf16 v[126:129], v[130:133], v[180:183], 0
	v_mfma_f32_16x16x32_bf16 v[122:125], v[138:141], v[180:183], 0
	v_mfma_f32_16x16x32_bf16 v[118:121], v[130:133], v[190:193], 0
	v_mfma_f32_16x16x32_bf16 v[110:113], v[138:141], v[190:193], 0
	v_mfma_f32_16x16x32_bf16 v[102:105], v[130:133], v[198:201], 0
	v_mfma_f32_16x16x32_bf16 v[94:97], v[138:141], v[198:201], 0
	v_mfma_f32_16x16x32_bf16 v[86:89], v[130:133], v[206:209], 0
	v_mfma_f32_16x16x32_bf16 v[78:81], v[138:141], v[206:209], 0
	v_mfma_f32_16x16x32_bf16 v[126:129], v[134:137], v[184:187], v[126:129]
	v_mfma_f32_16x16x32_bf16 v[122:125], v[142:145], v[184:187], v[122:125]
	v_mfma_f32_16x16x32_bf16 v[118:121], v[134:137], v[194:197], v[118:121]
	v_mfma_f32_16x16x32_bf16 v[110:113], v[142:145], v[194:197], v[110:113]
	v_mfma_f32_16x16x32_bf16 v[102:105], v[134:137], v[202:205], v[102:105]
	v_mfma_f32_16x16x32_bf16 v[94:97], v[142:145], v[202:205], v[94:97]
	v_mfma_f32_16x16x32_bf16 v[86:89], v[134:137], v[210:213], v[86:89]
	v_mfma_f32_16x16x32_bf16 v[78:81], v[142:145], v[210:213], v[78:81]
	s_barrier
	s_add_i32 s74, s66, s49
	s_add_u32 s98, s6, 0x80
	s_addc_u32 s99, s7, 0
	s_mov_b32 m0, s74
	ds_read_b128 v[214:217], v177
	ds_read_b128 v[218:221], v177 offset:1024
	ds_read_b128 v[222:225], v177 offset:2048
	global_load_lds_dwordx4 v148, s[6:7]
	s_add_i32 m0, s74, 0x2000
	ds_read_b128 v[226:229], v177 offset:3072
	global_load_lds_dwordx4 v152, s[6:7]
	s_barrier
	s_waitcnt lgkmcnt(0)
	v_mfma_f32_16x16x32_bf16 v[114:117], v[214:217], v[180:183], 0
	v_mfma_f32_16x16x32_bf16 v[106:109], v[222:225], v[180:183], 0
	v_mfma_f32_16x16x32_bf16 v[98:101], v[214:217], v[190:193], 0
	v_mfma_f32_16x16x32_bf16 v[90:93], v[222:225], v[190:193], 0
	v_mfma_f32_16x16x32_bf16 v[82:85], v[214:217], v[198:201], 0
	v_mfma_f32_16x16x32_bf16 v[74:77], v[222:225], v[198:201], 0
	v_mfma_f32_16x16x32_bf16 v[70:73], v[214:217], v[206:209], 0
	v_mfma_f32_16x16x32_bf16 v[66:69], v[222:225], v[206:209], 0
	v_mfma_f32_16x16x32_bf16 v[114:117], v[218:221], v[184:187], v[114:117]
	v_mfma_f32_16x16x32_bf16 v[106:109], v[226:229], v[184:187], v[106:109]
	v_mfma_f32_16x16x32_bf16 v[98:101], v[218:221], v[194:197], v[98:101]
	v_mfma_f32_16x16x32_bf16 v[90:93], v[226:229], v[194:197], v[90:93]
	v_mfma_f32_16x16x32_bf16 v[82:85], v[218:221], v[202:205], v[82:85]
	v_mfma_f32_16x16x32_bf16 v[74:77], v[226:229], v[202:205], v[74:77]
	v_mfma_f32_16x16x32_bf16 v[70:73], v[218:221], v[210:213], v[70:73]
	v_mfma_f32_16x16x32_bf16 v[66:69], v[226:229], v[210:213], v[66:69]
	s_mov_b32 m0, s50
	s_add_u32 s100, s8, 0x80
	s_addc_u32 s101, s9, 0
	s_barrier
	ds_read_b128 v[180:183], v175 offset:16384
	ds_read_b128 v[184:187], v175 offset:17408
	ds_read_b128 v[190:193], v175 offset:18432
	ds_read_b128 v[194:197], v175 offset:19456
	ds_read_b128 v[198:201], v175 offset:20480
	ds_read_b128 v[202:205], v175 offset:21504
	ds_read_b128 v[206:209], v175 offset:22528
	global_load_lds_dwordx4 v146, s[8:9]
	s_mov_b32 m0, s51
	ds_read_b128 v[210:213], v175 offset:23552
	global_load_lds_dwordx4 v150, s[8:9]
	s_barrier
	s_waitcnt lgkmcnt(0)
	v_mfma_f32_16x16x32_bf16 v[62:65], v[130:133], v[180:183], 0
	v_mfma_f32_16x16x32_bf16 v[58:61], v[138:141], v[180:183], 0
	v_mfma_f32_16x16x32_bf16 v[54:57], v[130:133], v[190:193], 0
	v_mfma_f32_16x16x32_bf16 v[46:49], v[138:141], v[190:193], 0
	v_mfma_f32_16x16x32_bf16 v[38:41], v[130:133], v[198:201], 0
	v_mfma_f32_16x16x32_bf16 v[30:33], v[138:141], v[198:201], 0
	v_mfma_f32_16x16x32_bf16 v[22:25], v[130:133], v[206:209], 0
	v_mfma_f32_16x16x32_bf16 v[14:17], v[138:141], v[206:209], 0
	v_mfma_f32_16x16x32_bf16 v[62:65], v[134:137], v[184:187], v[62:65]
	v_mfma_f32_16x16x32_bf16 v[58:61], v[142:145], v[184:187], v[58:61]
	v_mfma_f32_16x16x32_bf16 v[54:57], v[134:137], v[194:197], v[54:57]
	v_mfma_f32_16x16x32_bf16 v[46:49], v[142:145], v[194:197], v[46:49]
	v_mfma_f32_16x16x32_bf16 v[38:41], v[134:137], v[202:205], v[38:41]
	v_mfma_f32_16x16x32_bf16 v[30:33], v[142:145], v[202:205], v[30:33]
	v_mfma_f32_16x16x32_bf16 v[22:25], v[134:137], v[210:213], v[22:25]
	v_mfma_f32_16x16x32_bf16 v[14:17], v[142:145], v[210:213], v[14:17]
	s_barrier
	s_add_u32 s74, s6, 0x40000
	s_addc_u32 s75, s7, 0
	s_add_i32 s76, s67, s49
	s_mov_b32 m0, s76
	s_nop 0
	global_load_lds_dwordx4 v148, s[74:75]
	s_add_i32 m0, s76, 0x2000
	s_nop 0
	global_load_lds_dwordx4 v152, s[74:75]
	s_waitcnt vmcnt(6)
	s_barrier
	v_mfma_f32_16x16x32_bf16 v[50:53], v[214:217], v[180:183], 0
	v_mfma_f32_16x16x32_bf16 v[42:45], v[222:225], v[180:183], 0
	v_mfma_f32_16x16x32_bf16 v[34:37], v[214:217], v[190:193], 0
	v_mfma_f32_16x16x32_bf16 v[26:29], v[222:225], v[190:193], 0
	v_mfma_f32_16x16x32_bf16 v[18:21], v[214:217], v[198:201], 0
	v_mfma_f32_16x16x32_bf16 v[10:13], v[222:225], v[198:201], 0
	v_mfma_f32_16x16x32_bf16 v[6:9], v[214:217], v[206:209], 0
	v_mfma_f32_16x16x32_bf16 v[2:5], v[222:225], v[206:209], 0
	v_mfma_f32_16x16x32_bf16 v[50:53], v[218:221], v[184:187], v[50:53]
	v_mfma_f32_16x16x32_bf16 v[42:45], v[226:229], v[184:187], v[42:45]
	v_mfma_f32_16x16x32_bf16 v[34:37], v[218:221], v[194:197], v[34:37]
	v_mfma_f32_16x16x32_bf16 v[26:29], v[226:229], v[194:197], v[26:29]
	v_mfma_f32_16x16x32_bf16 v[18:21], v[218:221], v[202:205], v[18:21]
	v_mfma_f32_16x16x32_bf16 v[10:13], v[226:229], v[202:205], v[10:13]
	v_mfma_f32_16x16x32_bf16 v[6:9], v[218:221], v[210:213], v[6:9]
	v_mfma_f32_16x16x32_bf16 v[2:5], v[226:229], v[210:213], v[2:5]
	s_add_i32 s74, 0, 0x18000
	v_add_u32_e32 v142, s74, v171
	s_barrier
	ds_read_b128 v[130:133], v142
	ds_read_b128 v[134:137], v142 offset:1024
	ds_read_b128 v[138:141], v142 offset:2048
	ds_read_b128 v[142:145], v142 offset:3072
	s_add_u32 s8, s8, 0x40000
	s_addc_u32 s9, s9, 0
	s_mov_b32 m0, s52
	ds_read_b128 v[180:183], v175 offset:32768
	ds_read_b128 v[184:187], v175 offset:33792
	ds_read_b128 v[190:193], v175 offset:34816
	ds_read_b128 v[194:197], v175 offset:35840
	ds_read_b128 v[198:201], v175 offset:36864
	ds_read_b128 v[202:205], v175 offset:37888
	ds_read_b128 v[206:209], v175 offset:38912
	global_load_lds_dwordx4 v146, s[8:9]
	s_mov_b32 m0, s53
	ds_read_b128 v[210:213], v175 offset:39936
	global_load_lds_dwordx4 v150, s[8:9]
	s_waitcnt lgkmcnt(8)
	s_barrier
	s_waitcnt lgkmcnt(0)
	v_mfma_f32_16x16x32_bf16 v[126:129], v[130:133], v[180:183], v[126:129]
	v_mfma_f32_16x16x32_bf16 v[122:125], v[138:141], v[180:183], v[122:125]
	v_mfma_f32_16x16x32_bf16 v[118:121], v[130:133], v[190:193], v[118:121]
	v_mfma_f32_16x16x32_bf16 v[110:113], v[138:141], v[190:193], v[110:113]
	v_mfma_f32_16x16x32_bf16 v[102:105], v[130:133], v[198:201], v[102:105]
	v_mfma_f32_16x16x32_bf16 v[94:97], v[138:141], v[198:201], v[94:97]
	v_mfma_f32_16x16x32_bf16 v[86:89], v[130:133], v[206:209], v[86:89]
	v_mfma_f32_16x16x32_bf16 v[78:81], v[138:141], v[206:209], v[78:81]
	v_mfma_f32_16x16x32_bf16 v[126:129], v[134:137], v[184:187], v[126:129]
	v_mfma_f32_16x16x32_bf16 v[122:125], v[142:145], v[184:187], v[122:125]
	v_mfma_f32_16x16x32_bf16 v[118:121], v[134:137], v[194:197], v[118:121]
	v_mfma_f32_16x16x32_bf16 v[110:113], v[142:145], v[194:197], v[110:113]
	v_mfma_f32_16x16x32_bf16 v[102:105], v[134:137], v[202:205], v[102:105]
	v_mfma_f32_16x16x32_bf16 v[94:97], v[142:145], v[202:205], v[94:97]
	v_mfma_f32_16x16x32_bf16 v[86:89], v[134:137], v[210:213], v[86:89]
	v_mfma_f32_16x16x32_bf16 v[78:81], v[142:145], v[210:213], v[78:81]
	s_barrier
	s_add_i32 s8, 0, 0x1c000
	s_add_i32 s9, s74, s49
	v_add_u32_e32 v154, s8, v171
	s_mov_b32 m0, s9
	ds_read_b128 v[214:217], v154
	ds_read_b128 v[218:221], v154 offset:1024
	ds_read_b128 v[222:225], v154 offset:2048
	global_load_lds_dwordx4 v148, s[98:99]
	s_add_i32 m0, s9, 0x2000
	ds_read_b128 v[226:229], v154 offset:3072
	global_load_lds_dwordx4 v152, s[98:99]
	s_barrier
	s_waitcnt lgkmcnt(0)
	v_mfma_f32_16x16x32_bf16 v[114:117], v[214:217], v[180:183], v[114:117]
	v_mfma_f32_16x16x32_bf16 v[106:109], v[222:225], v[180:183], v[106:109]
	v_mfma_f32_16x16x32_bf16 v[98:101], v[214:217], v[190:193], v[98:101]
	v_mfma_f32_16x16x32_bf16 v[90:93], v[222:225], v[190:193], v[90:93]
	v_mfma_f32_16x16x32_bf16 v[82:85], v[214:217], v[198:201], v[82:85]
	v_mfma_f32_16x16x32_bf16 v[74:77], v[222:225], v[198:201], v[74:77]
	v_mfma_f32_16x16x32_bf16 v[70:73], v[214:217], v[206:209], v[70:73]
	v_mfma_f32_16x16x32_bf16 v[66:69], v[222:225], v[206:209], v[66:69]
	v_mfma_f32_16x16x32_bf16 v[114:117], v[218:221], v[184:187], v[114:117]
	v_mfma_f32_16x16x32_bf16 v[106:109], v[226:229], v[184:187], v[106:109]
	v_mfma_f32_16x16x32_bf16 v[98:101], v[218:221], v[194:197], v[98:101]
	v_mfma_f32_16x16x32_bf16 v[90:93], v[226:229], v[194:197], v[90:93]
	v_mfma_f32_16x16x32_bf16 v[82:85], v[218:221], v[202:205], v[82:85]
	v_mfma_f32_16x16x32_bf16 v[74:77], v[226:229], v[202:205], v[74:77]
	v_mfma_f32_16x16x32_bf16 v[70:73], v[218:221], v[210:213], v[70:73]
	v_mfma_f32_16x16x32_bf16 v[66:69], v[226:229], v[210:213], v[66:69]
	s_mov_b32 m0, s56
	s_barrier
	ds_read_b128 v[180:183], v175 offset:49152
	ds_read_b128 v[184:187], v175 offset:50176
	ds_read_b128 v[190:193], v175 offset:51200
	ds_read_b128 v[194:197], v175 offset:52224
	ds_read_b128 v[198:201], v175 offset:53248
	ds_read_b128 v[202:205], v175 offset:54272
	ds_read_b128 v[206:209], v175 offset:55296
	global_load_lds_dwordx4 v146, s[100:101]
	s_mov_b32 m0, s57
	ds_read_b128 v[210:213], v175 offset:56320
	global_load_lds_dwordx4 v150, s[100:101]
	s_barrier
	s_waitcnt lgkmcnt(0)
	v_mfma_f32_16x16x32_bf16 v[62:65], v[130:133], v[180:183], v[62:65]
	v_mfma_f32_16x16x32_bf16 v[58:61], v[138:141], v[180:183], v[58:61]
	v_mfma_f32_16x16x32_bf16 v[54:57], v[130:133], v[190:193], v[54:57]
	v_mfma_f32_16x16x32_bf16 v[46:49], v[138:141], v[190:193], v[46:49]
	v_mfma_f32_16x16x32_bf16 v[38:41], v[130:133], v[198:201], v[38:41]
	v_mfma_f32_16x16x32_bf16 v[30:33], v[138:141], v[198:201], v[30:33]
	v_mfma_f32_16x16x32_bf16 v[22:25], v[130:133], v[206:209], v[22:25]
	v_mfma_f32_16x16x32_bf16 v[14:17], v[138:141], v[206:209], v[14:17]
	v_mfma_f32_16x16x32_bf16 v[62:65], v[134:137], v[184:187], v[62:65]
	v_mfma_f32_16x16x32_bf16 v[58:61], v[142:145], v[184:187], v[58:61]
	v_mfma_f32_16x16x32_bf16 v[54:57], v[134:137], v[194:197], v[54:57]
	v_mfma_f32_16x16x32_bf16 v[46:49], v[142:145], v[194:197], v[46:49]
	v_mfma_f32_16x16x32_bf16 v[38:41], v[134:137], v[202:205], v[38:41]
	v_mfma_f32_16x16x32_bf16 v[30:33], v[142:145], v[202:205], v[30:33]
	v_mfma_f32_16x16x32_bf16 v[22:25], v[134:137], v[210:213], v[22:25]
	v_mfma_f32_16x16x32_bf16 v[14:17], v[142:145], v[210:213], v[14:17]
	s_barrier
	s_add_u32 s6, s6, 0x40080
	s_addc_u32 s7, s7, 0
	s_add_i32 s8, s8, s49
	s_mov_b32 m0, s8
	s_nop 0
	global_load_lds_dwordx4 v148, s[6:7]
	s_add_i32 m0, s8, 0x2000
	s_nop 0
	global_load_lds_dwordx4 v152, s[6:7]
	s_waitcnt vmcnt(6)
	s_barrier
	v_mfma_f32_16x16x32_bf16 v[50:53], v[214:217], v[180:183], v[50:53]
	v_mfma_f32_16x16x32_bf16 v[42:45], v[222:225], v[180:183], v[42:45]
	v_mfma_f32_16x16x32_bf16 v[34:37], v[214:217], v[190:193], v[34:37]
	v_mfma_f32_16x16x32_bf16 v[26:29], v[222:225], v[190:193], v[26:29]
	v_mfma_f32_16x16x32_bf16 v[18:21], v[214:217], v[198:201], v[18:21]
	v_mfma_f32_16x16x32_bf16 v[10:13], v[222:225], v[198:201], v[10:13]
	v_mfma_f32_16x16x32_bf16 v[6:9], v[214:217], v[206:209], v[6:9]
	v_mfma_f32_16x16x32_bf16 v[2:5], v[222:225], v[206:209], v[2:5]
	v_mfma_f32_16x16x32_bf16 v[50:53], v[218:221], v[184:187], v[50:53]
	v_mfma_f32_16x16x32_bf16 v[42:45], v[226:229], v[184:187], v[42:45]
	v_mfma_f32_16x16x32_bf16 v[34:37], v[218:221], v[194:197], v[34:37]
	v_mfma_f32_16x16x32_bf16 v[26:29], v[226:229], v[194:197], v[26:29]
	v_mfma_f32_16x16x32_bf16 v[18:21], v[218:221], v[202:205], v[18:21]
	v_mfma_f32_16x16x32_bf16 v[10:13], v[226:229], v[202:205], v[10:13]
	v_mfma_f32_16x16x32_bf16 v[6:9], v[218:221], v[210:213], v[6:9]
	v_mfma_f32_16x16x32_bf16 v[2:5], v[226:229], v[210:213], v[2:5]
	s_add_i32 s73, s73, 2
	s_add_u32 s2, s2, 0x100
	s_addc_u32 s3, s3, 0
	s_add_u32 s71, s71, 0x100
	s_addc_u32 s72, s72, 0
	s_cmp_gt_u32 s73, 13
	s_barrier
	s_cbranch_scc1 .Lpeel_p1_exit
.LBB0_212:
	ds_read_b128 v[130:133], v173
	ds_read_b128 v[134:137], v173 offset:1024
	ds_read_b128 v[138:141], v173 offset:2048
	ds_read_b128 v[142:145], v173 offset:3072
	s_add_u32 s6, s2, 0xfffc0080
	s_addc_u32 s7, s3, -1
	s_cmp_eq_u32 s73, 12
	s_cselect_b32 s9, s1, s7
	s_cselect_b32 s8, s33, s6
	s_cselect_b32 s7, s39, s72
	s_cselect_b32 s6, s41, s71
	s_add_i32 m0, s50, 0xc000
	ds_read_b128 v[180:183], v175
	ds_read_b128 v[184:187], v175 offset:1024
	ds_read_b128 v[190:193], v175 offset:2048
	ds_read_b128 v[194:197], v175 offset:3072
	ds_read_b128 v[198:201], v175 offset:4096
	ds_read_b128 v[202:205], v175 offset:5120
	ds_read_b128 v[206:209], v175 offset:6144
	global_load_lds_dwordx4 v156, s[2:3]
	s_add_i32 m0, s50, 0xe000
	ds_read_b128 v[210:213], v175 offset:7168
	global_load_lds_dwordx4 v158, s[2:3]
	s_waitcnt lgkmcnt(8)
	s_barrier
	s_waitcnt lgkmcnt(0)
	v_mfma_f32_16x16x32_bf16 v[126:129], v[130:133], v[180:183], v[126:129]
	v_mfma_f32_16x16x32_bf16 v[122:125], v[138:141], v[180:183], v[122:125]
	v_mfma_f32_16x16x32_bf16 v[118:121], v[130:133], v[190:193], v[118:121]
	v_mfma_f32_16x16x32_bf16 v[110:113], v[138:141], v[190:193], v[110:113]
	v_mfma_f32_16x16x32_bf16 v[102:105], v[130:133], v[198:201], v[102:105]
	v_mfma_f32_16x16x32_bf16 v[94:97], v[138:141], v[198:201], v[94:97]
	v_mfma_f32_16x16x32_bf16 v[86:89], v[130:133], v[206:209], v[86:89]
	v_mfma_f32_16x16x32_bf16 v[78:81], v[138:141], v[206:209], v[78:81]
	v_mfma_f32_16x16x32_bf16 v[126:129], v[134:137], v[184:187], v[126:129]
	v_mfma_f32_16x16x32_bf16 v[122:125], v[142:145], v[184:187], v[122:125]
	v_mfma_f32_16x16x32_bf16 v[118:121], v[134:137], v[194:197], v[118:121]
	v_mfma_f32_16x16x32_bf16 v[110:113], v[142:145], v[194:197], v[110:113]
	v_mfma_f32_16x16x32_bf16 v[102:105], v[134:137], v[202:205], v[102:105]
	v_mfma_f32_16x16x32_bf16 v[94:97], v[142:145], v[202:205], v[94:97]
	v_mfma_f32_16x16x32_bf16 v[86:89], v[134:137], v[210:213], v[86:89]
	v_mfma_f32_16x16x32_bf16 v[78:81], v[142:145], v[210:213], v[78:81]
	s_barrier
	s_add_i32 s74, s66, s49
	s_add_u32 s98, s6, 0x80
	s_addc_u32 s99, s7, 0
	s_mov_b32 m0, s74
	ds_read_b128 v[214:217], v177
	ds_read_b128 v[218:221], v177 offset:1024
	ds_read_b128 v[222:225], v177 offset:2048
	global_load_lds_dwordx4 v148, s[6:7]
	s_add_i32 m0, s74, 0x2000
	ds_read_b128 v[226:229], v177 offset:3072
	global_load_lds_dwordx4 v152, s[6:7]
	s_barrier
	s_waitcnt lgkmcnt(0)
	v_mfma_f32_16x16x32_bf16 v[114:117], v[214:217], v[180:183], v[114:117]
	v_mfma_f32_16x16x32_bf16 v[106:109], v[222:225], v[180:183], v[106:109]
	v_mfma_f32_16x16x32_bf16 v[98:101], v[214:217], v[190:193], v[98:101]
	v_mfma_f32_16x16x32_bf16 v[90:93], v[222:225], v[190:193], v[90:93]
	v_mfma_f32_16x16x32_bf16 v[82:85], v[214:217], v[198:201], v[82:85]
	v_mfma_f32_16x16x32_bf16 v[74:77], v[222:225], v[198:201], v[74:77]
	v_mfma_f32_16x16x32_bf16 v[70:73], v[214:217], v[206:209], v[70:73]
	v_mfma_f32_16x16x32_bf16 v[66:69], v[222:225], v[206:209], v[66:69]
	v_mfma_f32_16x16x32_bf16 v[114:117], v[218:221], v[184:187], v[114:117]
	v_mfma_f32_16x16x32_bf16 v[106:109], v[226:229], v[184:187], v[106:109]
	v_mfma_f32_16x16x32_bf16 v[98:101], v[218:221], v[194:197], v[98:101]
	v_mfma_f32_16x16x32_bf16 v[90:93], v[226:229], v[194:197], v[90:93]
	v_mfma_f32_16x16x32_bf16 v[82:85], v[218:221], v[202:205], v[82:85]
	v_mfma_f32_16x16x32_bf16 v[74:77], v[226:229], v[202:205], v[74:77]
	v_mfma_f32_16x16x32_bf16 v[70:73], v[218:221], v[210:213], v[70:73]
	v_mfma_f32_16x16x32_bf16 v[66:69], v[226:229], v[210:213], v[66:69]
	s_mov_b32 m0, s50
	s_add_u32 s100, s8, 0x80
	s_addc_u32 s101, s9, 0
	s_barrier
	ds_read_b128 v[180:183], v175 offset:16384
	ds_read_b128 v[184:187], v175 offset:17408
	ds_read_b128 v[190:193], v175 offset:18432
	ds_read_b128 v[194:197], v175 offset:19456
	ds_read_b128 v[198:201], v175 offset:20480
	ds_read_b128 v[202:205], v175 offset:21504
	ds_read_b128 v[206:209], v175 offset:22528
	global_load_lds_dwordx4 v146, s[8:9]
	s_mov_b32 m0, s51
	ds_read_b128 v[210:213], v175 offset:23552
	global_load_lds_dwordx4 v150, s[8:9]
	s_barrier
	s_waitcnt lgkmcnt(0)
	v_mfma_f32_16x16x32_bf16 v[62:65], v[130:133], v[180:183], v[62:65]
	v_mfma_f32_16x16x32_bf16 v[58:61], v[138:141], v[180:183], v[58:61]
	v_mfma_f32_16x16x32_bf16 v[54:57], v[130:133], v[190:193], v[54:57]
	v_mfma_f32_16x16x32_bf16 v[46:49], v[138:141], v[190:193], v[46:49]
	v_mfma_f32_16x16x32_bf16 v[38:41], v[130:133], v[198:201], v[38:41]
	v_mfma_f32_16x16x32_bf16 v[30:33], v[138:141], v[198:201], v[30:33]
	v_mfma_f32_16x16x32_bf16 v[22:25], v[130:133], v[206:209], v[22:25]
	v_mfma_f32_16x16x32_bf16 v[14:17], v[138:141], v[206:209], v[14:17]
	v_mfma_f32_16x16x32_bf16 v[62:65], v[134:137], v[184:187], v[62:65]
	v_mfma_f32_16x16x32_bf16 v[58:61], v[142:145], v[184:187], v[58:61]
	v_mfma_f32_16x16x32_bf16 v[54:57], v[134:137], v[194:197], v[54:57]
	v_mfma_f32_16x16x32_bf16 v[46:49], v[142:145], v[194:197], v[46:49]
	v_mfma_f32_16x16x32_bf16 v[38:41], v[134:137], v[202:205], v[38:41]
	v_mfma_f32_16x16x32_bf16 v[30:33], v[142:145], v[202:205], v[30:33]
	v_mfma_f32_16x16x32_bf16 v[22:25], v[134:137], v[210:213], v[22:25]
	v_mfma_f32_16x16x32_bf16 v[14:17], v[142:145], v[210:213], v[14:17]
	s_barrier
	s_add_u32 s74, s6, 0x40000
	s_addc_u32 s75, s7, 0
	s_add_i32 s76, s67, s49
	s_mov_b32 m0, s76
	s_nop 0
	global_load_lds_dwordx4 v148, s[74:75]
	s_add_i32 m0, s76, 0x2000
	s_nop 0
	global_load_lds_dwordx4 v152, s[74:75]
	s_waitcnt vmcnt(6)
	s_barrier
	v_mfma_f32_16x16x32_bf16 v[50:53], v[214:217], v[180:183], v[50:53]
	v_mfma_f32_16x16x32_bf16 v[42:45], v[222:225], v[180:183], v[42:45]
	v_mfma_f32_16x16x32_bf16 v[34:37], v[214:217], v[190:193], v[34:37]
	v_mfma_f32_16x16x32_bf16 v[26:29], v[222:225], v[190:193], v[26:29]
	v_mfma_f32_16x16x32_bf16 v[18:21], v[214:217], v[198:201], v[18:21]
	v_mfma_f32_16x16x32_bf16 v[10:13], v[222:225], v[198:201], v[10:13]
	v_mfma_f32_16x16x32_bf16 v[6:9], v[214:217], v[206:209], v[6:9]
	v_mfma_f32_16x16x32_bf16 v[2:5], v[222:225], v[206:209], v[2:5]
	v_mfma_f32_16x16x32_bf16 v[50:53], v[218:221], v[184:187], v[50:53]
	v_mfma_f32_16x16x32_bf16 v[42:45], v[226:229], v[184:187], v[42:45]
	v_mfma_f32_16x16x32_bf16 v[34:37], v[218:221], v[194:197], v[34:37]
	v_mfma_f32_16x16x32_bf16 v[26:29], v[226:229], v[194:197], v[26:29]
	v_mfma_f32_16x16x32_bf16 v[18:21], v[218:221], v[202:205], v[18:21]
	v_mfma_f32_16x16x32_bf16 v[10:13], v[226:229], v[202:205], v[10:13]
	v_mfma_f32_16x16x32_bf16 v[6:9], v[218:221], v[210:213], v[6:9]
	v_mfma_f32_16x16x32_bf16 v[2:5], v[226:229], v[210:213], v[2:5]
	s_add_i32 s74, 0, 0x18000
	v_add_u32_e32 v142, s74, v171
	s_barrier
	ds_read_b128 v[130:133], v142
	ds_read_b128 v[134:137], v142 offset:1024
	ds_read_b128 v[138:141], v142 offset:2048
	ds_read_b128 v[142:145], v142 offset:3072
	s_add_u32 s8, s8, 0x40000
	s_addc_u32 s9, s9, 0
	s_mov_b32 m0, s52
	ds_read_b128 v[180:183], v175 offset:32768
	ds_read_b128 v[184:187], v175 offset:33792
	ds_read_b128 v[190:193], v175 offset:34816
	ds_read_b128 v[194:197], v175 offset:35840
	ds_read_b128 v[198:201], v175 offset:36864
	ds_read_b128 v[202:205], v175 offset:37888
	ds_read_b128 v[206:209], v175 offset:38912
	global_load_lds_dwordx4 v146, s[8:9]
	s_mov_b32 m0, s53
	ds_read_b128 v[210:213], v175 offset:39936
	global_load_lds_dwordx4 v150, s[8:9]
	s_waitcnt lgkmcnt(8)
	s_barrier
	s_waitcnt lgkmcnt(0)
	v_mfma_f32_16x16x32_bf16 v[126:129], v[130:133], v[180:183], v[126:129]
	v_mfma_f32_16x16x32_bf16 v[122:125], v[138:141], v[180:183], v[122:125]
	v_mfma_f32_16x16x32_bf16 v[118:121], v[130:133], v[190:193], v[118:121]
	v_mfma_f32_16x16x32_bf16 v[110:113], v[138:141], v[190:193], v[110:113]
	v_mfma_f32_16x16x32_bf16 v[102:105], v[130:133], v[198:201], v[102:105]
	v_mfma_f32_16x16x32_bf16 v[94:97], v[138:141], v[198:201], v[94:97]
	v_mfma_f32_16x16x32_bf16 v[86:89], v[130:133], v[206:209], v[86:89]
	v_mfma_f32_16x16x32_bf16 v[78:81], v[138:141], v[206:209], v[78:81]
	v_mfma_f32_16x16x32_bf16 v[126:129], v[134:137], v[184:187], v[126:129]
	v_mfma_f32_16x16x32_bf16 v[122:125], v[142:145], v[184:187], v[122:125]
	v_mfma_f32_16x16x32_bf16 v[118:121], v[134:137], v[194:197], v[118:121]
	v_mfma_f32_16x16x32_bf16 v[110:113], v[142:145], v[194:197], v[110:113]
	v_mfma_f32_16x16x32_bf16 v[102:105], v[134:137], v[202:205], v[102:105]
	v_mfma_f32_16x16x32_bf16 v[94:97], v[142:145], v[202:205], v[94:97]
	v_mfma_f32_16x16x32_bf16 v[86:89], v[134:137], v[210:213], v[86:89]
	v_mfma_f32_16x16x32_bf16 v[78:81], v[142:145], v[210:213], v[78:81]
	s_barrier
	s_add_i32 s8, 0, 0x1c000
	s_add_i32 s9, s74, s49
	v_add_u32_e32 v154, s8, v171
	s_mov_b32 m0, s9
	ds_read_b128 v[214:217], v154
	ds_read_b128 v[218:221], v154 offset:1024
	ds_read_b128 v[222:225], v154 offset:2048
	global_load_lds_dwordx4 v148, s[98:99]
	s_add_i32 m0, s9, 0x2000
	ds_read_b128 v[226:229], v154 offset:3072
	global_load_lds_dwordx4 v152, s[98:99]
	s_barrier
	s_waitcnt lgkmcnt(0)
	v_mfma_f32_16x16x32_bf16 v[114:117], v[214:217], v[180:183], v[114:117]
	v_mfma_f32_16x16x32_bf16 v[106:109], v[222:225], v[180:183], v[106:109]
	v_mfma_f32_16x16x32_bf16 v[98:101], v[214:217], v[190:193], v[98:101]
	v_mfma_f32_16x16x32_bf16 v[90:93], v[222:225], v[190:193], v[90:93]
	v_mfma_f32_16x16x32_bf16 v[82:85], v[214:217], v[198:201], v[82:85]
	v_mfma_f32_16x16x32_bf16 v[74:77], v[222:225], v[198:201], v[74:77]
	v_mfma_f32_16x16x32_bf16 v[70:73], v[214:217], v[206:209], v[70:73]
	v_mfma_f32_16x16x32_bf16 v[66:69], v[222:225], v[206:209], v[66:69]
	v_mfma_f32_16x16x32_bf16 v[114:117], v[218:221], v[184:187], v[114:117]
	v_mfma_f32_16x16x32_bf16 v[106:109], v[226:229], v[184:187], v[106:109]
	v_mfma_f32_16x16x32_bf16 v[98:101], v[218:221], v[194:197], v[98:101]
	v_mfma_f32_16x16x32_bf16 v[90:93], v[226:229], v[194:197], v[90:93]
	v_mfma_f32_16x16x32_bf16 v[82:85], v[218:221], v[202:205], v[82:85]
	v_mfma_f32_16x16x32_bf16 v[74:77], v[226:229], v[202:205], v[74:77]
	v_mfma_f32_16x16x32_bf16 v[70:73], v[218:221], v[210:213], v[70:73]
	v_mfma_f32_16x16x32_bf16 v[66:69], v[226:229], v[210:213], v[66:69]
	s_mov_b32 m0, s56
	s_barrier
	ds_read_b128 v[180:183], v175 offset:49152
	ds_read_b128 v[184:187], v175 offset:50176
	ds_read_b128 v[190:193], v175 offset:51200
	ds_read_b128 v[194:197], v175 offset:52224
	ds_read_b128 v[198:201], v175 offset:53248
	ds_read_b128 v[202:205], v175 offset:54272
	ds_read_b128 v[206:209], v175 offset:55296
	global_load_lds_dwordx4 v146, s[100:101]
	s_mov_b32 m0, s57
	ds_read_b128 v[210:213], v175 offset:56320
	global_load_lds_dwordx4 v150, s[100:101]
	s_barrier
	s_waitcnt lgkmcnt(0)
	v_mfma_f32_16x16x32_bf16 v[62:65], v[130:133], v[180:183], v[62:65]
	v_mfma_f32_16x16x32_bf16 v[58:61], v[138:141], v[180:183], v[58:61]
	v_mfma_f32_16x16x32_bf16 v[54:57], v[130:133], v[190:193], v[54:57]
	v_mfma_f32_16x16x32_bf16 v[46:49], v[138:141], v[190:193], v[46:49]
	v_mfma_f32_16x16x32_bf16 v[38:41], v[130:133], v[198:201], v[38:41]
	v_mfma_f32_16x16x32_bf16 v[30:33], v[138:141], v[198:201], v[30:33]
	v_mfma_f32_16x16x32_bf16 v[22:25], v[130:133], v[206:209], v[22:25]
	v_mfma_f32_16x16x32_bf16 v[14:17], v[138:141], v[206:209], v[14:17]
	v_mfma_f32_16x16x32_bf16 v[62:65], v[134:137], v[184:187], v[62:65]
	v_mfma_f32_16x16x32_bf16 v[58:61], v[142:145], v[184:187], v[58:61]
	v_mfma_f32_16x16x32_bf16 v[54:57], v[134:137], v[194:197], v[54:57]
	v_mfma_f32_16x16x32_bf16 v[46:49], v[142:145], v[194:197], v[46:49]
	v_mfma_f32_16x16x32_bf16 v[38:41], v[134:137], v[202:205], v[38:41]
	v_mfma_f32_16x16x32_bf16 v[30:33], v[142:145], v[202:205], v[30:33]
	v_mfma_f32_16x16x32_bf16 v[22:25], v[134:137], v[210:213], v[22:25]
	v_mfma_f32_16x16x32_bf16 v[14:17], v[142:145], v[210:213], v[14:17]
	s_barrier
	s_add_u32 s6, s6, 0x40080
	s_addc_u32 s7, s7, 0
	s_add_i32 s8, s8, s49
	s_mov_b32 m0, s8
	s_nop 0
	global_load_lds_dwordx4 v148, s[6:7]
	s_add_i32 m0, s8, 0x2000
	s_nop 0
	global_load_lds_dwordx4 v152, s[6:7]
	s_waitcnt vmcnt(6)
	s_barrier
	v_mfma_f32_16x16x32_bf16 v[50:53], v[214:217], v[180:183], v[50:53]
	v_mfma_f32_16x16x32_bf16 v[42:45], v[222:225], v[180:183], v[42:45]
	v_mfma_f32_16x16x32_bf16 v[34:37], v[214:217], v[190:193], v[34:37]
	v_mfma_f32_16x16x32_bf16 v[26:29], v[222:225], v[190:193], v[26:29]
	v_mfma_f32_16x16x32_bf16 v[18:21], v[214:217], v[198:201], v[18:21]
	v_mfma_f32_16x16x32_bf16 v[10:13], v[222:225], v[198:201], v[10:13]
	v_mfma_f32_16x16x32_bf16 v[6:9], v[214:217], v[206:209], v[6:9]
	v_mfma_f32_16x16x32_bf16 v[2:5], v[222:225], v[206:209], v[2:5]
	v_mfma_f32_16x16x32_bf16 v[50:53], v[218:221], v[184:187], v[50:53]
	v_mfma_f32_16x16x32_bf16 v[42:45], v[226:229], v[184:187], v[42:45]
	v_mfma_f32_16x16x32_bf16 v[34:37], v[218:221], v[194:197], v[34:37]
	v_mfma_f32_16x16x32_bf16 v[26:29], v[226:229], v[194:197], v[26:29]
	v_mfma_f32_16x16x32_bf16 v[18:21], v[218:221], v[202:205], v[18:21]
	v_mfma_f32_16x16x32_bf16 v[10:13], v[226:229], v[202:205], v[10:13]
	v_mfma_f32_16x16x32_bf16 v[6:9], v[218:221], v[210:213], v[6:9]
	v_mfma_f32_16x16x32_bf16 v[2:5], v[226:229], v[210:213], v[2:5]
	s_add_i32 s73, s73, 2
	s_add_u32 s2, s2, 0x100
	s_addc_u32 s3, s3, 0
	s_add_u32 s71, s71, 0x100
	s_addc_u32 s72, s72, 0
	s_cmp_gt_u32 s73, 13
	s_barrier
	s_cbranch_scc0 .LBB0_212

.Lpeel_p8:
	ds_read_b128 v[130:133], v181
	ds_read_b128 v[134:137], v181 offset:1024
	ds_read_b128 v[138:141], v181 offset:2048
	ds_read_b128 v[142:145], v181 offset:3072
	s_add_u32 s2, s0, 0xfffc0080
	s_addc_u32 s3, s1, -1
	s_cmp_eq_u32 s74, 12
	s_cselect_b32 s45, s33, s3
	s_cselect_b32 s44, s39, s2
	s_cselect_b32 s3, s37, s73
	s_cselect_b32 s2, s71, s72
	s_add_i32 m0, s52, 0xc000
	ds_read_b128 v[146:149], v183
	ds_read_b128 v[150:153], v183 offset:1024
	ds_read_b128 v[154:157], v183 offset:2048
	ds_read_b128 v[158:161], v183 offset:3072
	ds_read_b128 v[162:165], v183 offset:4096
	ds_read_b128 v[166:169], v183 offset:5120
	ds_read_b128 v[170:173], v183 offset:6144
	global_load_lds_dwordx4 v192, s[0:1]
	s_add_i32 m0, s52, 0xe000
	ds_read_b128 v[174:177], v183 offset:7168
	global_load_lds_dwordx4 v194, s[0:1]
	s_waitcnt lgkmcnt(8)
	s_barrier
	s_waitcnt lgkmcnt(0)
	v_mfma_f32_16x16x32_bf16 v[62:65], v[130:133], v[146:149], 0
	v_mfma_f32_16x16x32_bf16 v[30:33], v[138:141], v[146:149], 0
	v_mfma_f32_16x16x32_bf16 v[54:57], v[130:133], v[154:157], 0
	v_mfma_f32_16x16x32_bf16 v[22:25], v[138:141], v[154:157], 0
	v_mfma_f32_16x16x32_bf16 v[46:49], v[130:133], v[162:165], 0
	v_mfma_f32_16x16x32_bf16 v[14:17], v[138:141], v[162:165], 0
	v_mfma_f32_16x16x32_bf16 v[38:41], v[130:133], v[170:173], 0
	v_mfma_f32_16x16x32_bf16 v[6:9], v[138:141], v[170:173], 0
	v_mfma_f32_16x16x32_bf16 v[62:65], v[134:137], v[150:153], v[62:65]
	v_mfma_f32_16x16x32_bf16 v[30:33], v[142:145], v[150:153], v[30:33]
	v_mfma_f32_16x16x32_bf16 v[54:57], v[134:137], v[158:161], v[54:57]
	v_mfma_f32_16x16x32_bf16 v[22:25], v[142:145], v[158:161], v[22:25]
	v_mfma_f32_16x16x32_bf16 v[46:49], v[134:137], v[166:169], v[46:49]
	v_mfma_f32_16x16x32_bf16 v[14:17], v[142:145], v[166:169], v[14:17]
	v_mfma_f32_16x16x32_bf16 v[38:41], v[134:137], v[174:177], v[38:41]
	v_mfma_f32_16x16x32_bf16 v[6:9], v[142:145], v[174:177], v[6:9]
	s_barrier
	s_add_i32 s75, s66, s51
	s_add_u32 s98, s2, 0x80
	s_addc_u32 s99, s3, 0
	s_mov_b32 m0, s75
	ds_read_b128 v[200:203], v206
	ds_read_b128 v[212:215], v206 offset:1024
	ds_read_b128 v[216:219], v206 offset:2048
	global_load_lds_dwordx4 v186, s[2:3]
	s_add_i32 m0, s75, 0x2000
	ds_read_b128 v[220:223], v206 offset:3072
	global_load_lds_dwordx4 v190, s[2:3]
	s_barrier
	s_waitcnt lgkmcnt(0)
	v_mfma_f32_16x16x32_bf16 v[58:61], v[200:203], v[146:149], 0
	v_mfma_f32_16x16x32_bf16 v[26:29], v[216:219], v[146:149], 0
	v_mfma_f32_16x16x32_bf16 v[50:53], v[200:203], v[154:157], 0
	v_mfma_f32_16x16x32_bf16 v[18:21], v[216:219], v[154:157], 0
	v_mfma_f32_16x16x32_bf16 v[42:45], v[200:203], v[162:165], 0
	v_mfma_f32_16x16x32_bf16 v[10:13], v[216:219], v[162:165], 0
	v_mfma_f32_16x16x32_bf16 v[34:37], v[200:203], v[170:173], 0
	v_mfma_f32_16x16x32_bf16 v[2:5], v[216:219], v[170:173], 0
	v_mfma_f32_16x16x32_bf16 v[58:61], v[212:215], v[150:153], v[58:61]
	v_mfma_f32_16x16x32_bf16 v[26:29], v[220:223], v[150:153], v[26:29]
	v_mfma_f32_16x16x32_bf16 v[50:53], v[212:215], v[158:161], v[50:53]
	v_mfma_f32_16x16x32_bf16 v[18:21], v[220:223], v[158:161], v[18:21]
	v_mfma_f32_16x16x32_bf16 v[42:45], v[212:215], v[166:169], v[42:45]
	v_mfma_f32_16x16x32_bf16 v[10:13], v[220:223], v[166:169], v[10:13]
	v_mfma_f32_16x16x32_bf16 v[34:37], v[212:215], v[174:177], v[34:37]
	v_mfma_f32_16x16x32_bf16 v[2:5], v[220:223], v[174:177], v[2:5]
	s_mov_b32 m0, s52
	s_add_u32 s100, s44, 0x80
	s_addc_u32 s101, s45, 0
	s_barrier
	ds_read_b128 v[146:149], v183 offset:16384
	ds_read_b128 v[150:153], v183 offset:17408
	ds_read_b128 v[154:157], v183 offset:18432
	ds_read_b128 v[158:161], v183 offset:19456
	ds_read_b128 v[162:165], v183 offset:20480
	ds_read_b128 v[166:169], v183 offset:21504
	ds_read_b128 v[170:173], v183 offset:22528
	global_load_lds_dwordx4 v184, s[44:45]
	s_mov_b32 m0, s53
	ds_read_b128 v[174:177], v183 offset:23552
	global_load_lds_dwordx4 v188, s[44:45]
	s_barrier
	s_waitcnt lgkmcnt(0)
	v_mfma_f32_16x16x32_bf16 v[126:129], v[130:133], v[146:149], 0
	v_mfma_f32_16x16x32_bf16 v[102:105], v[138:141], v[146:149], 0
	v_mfma_f32_16x16x32_bf16 v[122:125], v[130:133], v[154:157], 0
	v_mfma_f32_16x16x32_bf16 v[90:93], v[138:141], v[154:157], 0
	v_mfma_f32_16x16x32_bf16 v[118:121], v[130:133], v[162:165], 0
	v_mfma_f32_16x16x32_bf16 v[78:81], v[138:141], v[162:165], 0
	v_mfma_f32_16x16x32_bf16 v[106:109], v[130:133], v[170:173], 0
	v_mfma_f32_16x16x32_bf16 v[70:73], v[138:141], v[170:173], 0
	v_mfma_f32_16x16x32_bf16 v[126:129], v[134:137], v[150:153], v[126:129]
	v_mfma_f32_16x16x32_bf16 v[102:105], v[142:145], v[150:153], v[102:105]
	v_mfma_f32_16x16x32_bf16 v[122:125], v[134:137], v[158:161], v[122:125]
	v_mfma_f32_16x16x32_bf16 v[90:93], v[142:145], v[158:161], v[90:93]
	v_mfma_f32_16x16x32_bf16 v[118:121], v[134:137], v[166:169], v[118:121]
	v_mfma_f32_16x16x32_bf16 v[78:81], v[142:145], v[166:169], v[78:81]
	v_mfma_f32_16x16x32_bf16 v[106:109], v[134:137], v[174:177], v[106:109]
	v_mfma_f32_16x16x32_bf16 v[70:73], v[142:145], v[174:177], v[70:73]
	s_barrier
	s_add_u32 s76, s2, 0x40000
	s_addc_u32 s77, s3, 0
	s_add_i32 s75, s67, s51
	s_mov_b32 m0, s75
	s_nop 0
	global_load_lds_dwordx4 v186, s[76:77]
	s_add_i32 m0, s75, 0x2000
	s_nop 0
	global_load_lds_dwordx4 v190, s[76:77]
	s_waitcnt vmcnt(6)
	s_barrier
	v_mfma_f32_16x16x32_bf16 v[114:117], v[200:203], v[146:149], 0
	v_mfma_f32_16x16x32_bf16 v[86:89], v[216:219], v[146:149], 0
	v_mfma_f32_16x16x32_bf16 v[110:113], v[200:203], v[154:157], 0
	v_mfma_f32_16x16x32_bf16 v[82:85], v[216:219], v[154:157], 0
	v_mfma_f32_16x16x32_bf16 v[98:101], v[200:203], v[162:165], 0
	v_mfma_f32_16x16x32_bf16 v[74:77], v[216:219], v[162:165], 0
	v_mfma_f32_16x16x32_bf16 v[94:97], v[200:203], v[170:173], 0
	v_mfma_f32_16x16x32_bf16 v[66:69], v[216:219], v[170:173], 0
	v_mfma_f32_16x16x32_bf16 v[114:117], v[212:215], v[150:153], v[114:117]
	v_mfma_f32_16x16x32_bf16 v[86:89], v[220:223], v[150:153], v[86:89]
	v_mfma_f32_16x16x32_bf16 v[110:113], v[212:215], v[158:161], v[110:113]
	v_mfma_f32_16x16x32_bf16 v[82:85], v[220:223], v[158:161], v[82:85]
	v_mfma_f32_16x16x32_bf16 v[98:101], v[212:215], v[166:169], v[98:101]
	v_mfma_f32_16x16x32_bf16 v[74:77], v[220:223], v[166:169], v[74:77]
	v_mfma_f32_16x16x32_bf16 v[94:97], v[212:215], v[174:177], v[94:97]
	v_mfma_f32_16x16x32_bf16 v[66:69], v[220:223], v[174:177], v[66:69]
	s_add_i32 s75, 0, 0x18000
	v_add_u32_e32 v142, s75, v1
	s_barrier
	ds_read_b128 v[130:133], v142
	ds_read_b128 v[134:137], v142 offset:1024
	ds_read_b128 v[138:141], v142 offset:2048
	ds_read_b128 v[142:145], v142 offset:3072
	s_add_u32 s44, s44, 0x40000
	s_addc_u32 s45, s45, 0
	s_mov_b32 m0, s54
	ds_read_b128 v[146:149], v183 offset:32768
	ds_read_b128 v[150:153], v183 offset:33792
	ds_read_b128 v[154:157], v183 offset:34816
	ds_read_b128 v[158:161], v183 offset:35840
	ds_read_b128 v[162:165], v183 offset:36864
	ds_read_b128 v[166:169], v183 offset:37888
	ds_read_b128 v[170:173], v183 offset:38912
	global_load_lds_dwordx4 v184, s[44:45]
	s_mov_b32 m0, s55
	ds_read_b128 v[174:177], v183 offset:39936
	global_load_lds_dwordx4 v188, s[44:45]
	s_waitcnt lgkmcnt(8)
	s_barrier
	s_waitcnt lgkmcnt(0)
	v_mfma_f32_16x16x32_bf16 v[62:65], v[130:133], v[146:149], v[62:65]
	v_mfma_f32_16x16x32_bf16 v[30:33], v[138:141], v[146:149], v[30:33]
	v_mfma_f32_16x16x32_bf16 v[54:57], v[130:133], v[154:157], v[54:57]
	v_mfma_f32_16x16x32_bf16 v[22:25], v[138:141], v[154:157], v[22:25]
	v_mfma_f32_16x16x32_bf16 v[46:49], v[130:133], v[162:165], v[46:49]
	v_mfma_f32_16x16x32_bf16 v[14:17], v[138:141], v[162:165], v[14:17]
	v_mfma_f32_16x16x32_bf16 v[38:41], v[130:133], v[170:173], v[38:41]
	v_mfma_f32_16x16x32_bf16 v[6:9], v[138:141], v[170:173], v[6:9]
	v_mfma_f32_16x16x32_bf16 v[62:65], v[134:137], v[150:153], v[62:65]
	v_mfma_f32_16x16x32_bf16 v[30:33], v[142:145], v[150:153], v[30:33]
	v_mfma_f32_16x16x32_bf16 v[54:57], v[134:137], v[158:161], v[54:57]
	v_mfma_f32_16x16x32_bf16 v[22:25], v[142:145], v[158:161], v[22:25]
	v_mfma_f32_16x16x32_bf16 v[46:49], v[134:137], v[166:169], v[46:49]
	v_mfma_f32_16x16x32_bf16 v[14:17], v[142:145], v[166:169], v[14:17]
	v_mfma_f32_16x16x32_bf16 v[38:41], v[134:137], v[174:177], v[38:41]
	v_mfma_f32_16x16x32_bf16 v[6:9], v[142:145], v[174:177], v[6:9]
	s_barrier
	s_add_i32 s44, 0, 0x1c000
	s_add_i32 s45, s75, s51
	v_add_u32_e32 v207, s44, v1
	s_mov_b32 m0, s45
	ds_read_b128 v[200:203], v207
	ds_read_b128 v[212:215], v207 offset:1024
	ds_read_b128 v[216:219], v207 offset:2048
	global_load_lds_dwordx4 v186, s[98:99]
	s_add_i32 m0, s45, 0x2000
	ds_read_b128 v[220:223], v207 offset:3072
	global_load_lds_dwordx4 v190, s[98:99]
	s_barrier
	s_waitcnt lgkmcnt(0)
	v_mfma_f32_16x16x32_bf16 v[58:61], v[200:203], v[146:149], v[58:61]
	v_mfma_f32_16x16x32_bf16 v[26:29], v[216:219], v[146:149], v[26:29]
	v_mfma_f32_16x16x32_bf16 v[50:53], v[200:203], v[154:157], v[50:53]
	v_mfma_f32_16x16x32_bf16 v[18:21], v[216:219], v[154:157], v[18:21]
	v_mfma_f32_16x16x32_bf16 v[42:45], v[200:203], v[162:165], v[42:45]
	v_mfma_f32_16x16x32_bf16 v[10:13], v[216:219], v[162:165], v[10:13]
	v_mfma_f32_16x16x32_bf16 v[34:37], v[200:203], v[170:173], v[34:37]
	v_mfma_f32_16x16x32_bf16 v[2:5], v[216:219], v[170:173], v[2:5]
	v_mfma_f32_16x16x32_bf16 v[58:61], v[212:215], v[150:153], v[58:61]
	v_mfma_f32_16x16x32_bf16 v[26:29], v[220:223], v[150:153], v[26:29]
	v_mfma_f32_16x16x32_bf16 v[50:53], v[212:215], v[158:161], v[50:53]
	v_mfma_f32_16x16x32_bf16 v[18:21], v[220:223], v[158:161], v[18:21]
	v_mfma_f32_16x16x32_bf16 v[42:45], v[212:215], v[166:169], v[42:45]
	v_mfma_f32_16x16x32_bf16 v[10:13], v[220:223], v[166:169], v[10:13]
	v_mfma_f32_16x16x32_bf16 v[34:37], v[212:215], v[174:177], v[34:37]
	v_mfma_f32_16x16x32_bf16 v[2:5], v[220:223], v[174:177], v[2:5]
	s_mov_b32 m0, s59
	s_barrier
	ds_read_b128 v[146:149], v183 offset:49152
	ds_read_b128 v[150:153], v183 offset:50176
	ds_read_b128 v[154:157], v183 offset:51200
	ds_read_b128 v[158:161], v183 offset:52224
	ds_read_b128 v[162:165], v183 offset:53248
	ds_read_b128 v[166:169], v183 offset:54272
	ds_read_b128 v[170:173], v183 offset:55296
	global_load_lds_dwordx4 v184, s[100:101]
	s_mov_b32 m0, s60
	ds_read_b128 v[174:177], v183 offset:56320
	global_load_lds_dwordx4 v188, s[100:101]
	s_barrier
	s_waitcnt lgkmcnt(0)
	v_mfma_f32_16x16x32_bf16 v[126:129], v[130:133], v[146:149], v[126:129]
	v_mfma_f32_16x16x32_bf16 v[102:105], v[138:141], v[146:149], v[102:105]
	v_mfma_f32_16x16x32_bf16 v[122:125], v[130:133], v[154:157], v[122:125]
	v_mfma_f32_16x16x32_bf16 v[90:93], v[138:141], v[154:157], v[90:93]
	v_mfma_f32_16x16x32_bf16 v[118:121], v[130:133], v[162:165], v[118:121]
	v_mfma_f32_16x16x32_bf16 v[78:81], v[138:141], v[162:165], v[78:81]
	v_mfma_f32_16x16x32_bf16 v[106:109], v[130:133], v[170:173], v[106:109]
	v_mfma_f32_16x16x32_bf16 v[70:73], v[138:141], v[170:173], v[70:73]
	v_mfma_f32_16x16x32_bf16 v[126:129], v[134:137], v[150:153], v[126:129]
	v_mfma_f32_16x16x32_bf16 v[102:105], v[142:145], v[150:153], v[102:105]
	v_mfma_f32_16x16x32_bf16 v[122:125], v[134:137], v[158:161], v[122:125]
	v_mfma_f32_16x16x32_bf16 v[90:93], v[142:145], v[158:161], v[90:93]
	v_mfma_f32_16x16x32_bf16 v[118:121], v[134:137], v[166:169], v[118:121]
	v_mfma_f32_16x16x32_bf16 v[78:81], v[142:145], v[166:169], v[78:81]
	v_mfma_f32_16x16x32_bf16 v[106:109], v[134:137], v[174:177], v[106:109]
	v_mfma_f32_16x16x32_bf16 v[70:73], v[142:145], v[174:177], v[70:73]
	s_barrier
	s_add_u32 s2, s2, 0x40080
	s_addc_u32 s3, s3, 0
	s_add_i32 s44, s44, s51
	s_mov_b32 m0, s44
	s_nop 0
	global_load_lds_dwordx4 v186, s[2:3]
	s_add_i32 m0, s44, 0x2000
	s_nop 0
	global_load_lds_dwordx4 v190, s[2:3]
	s_waitcnt vmcnt(6)
	s_barrier
	v_mfma_f32_16x16x32_bf16 v[114:117], v[200:203], v[146:149], v[114:117]
	v_mfma_f32_16x16x32_bf16 v[86:89], v[216:219], v[146:149], v[86:89]
	v_mfma_f32_16x16x32_bf16 v[110:113], v[200:203], v[154:157], v[110:113]
	v_mfma_f32_16x16x32_bf16 v[82:85], v[216:219], v[154:157], v[82:85]
	v_mfma_f32_16x16x32_bf16 v[98:101], v[200:203], v[162:165], v[98:101]
	v_mfma_f32_16x16x32_bf16 v[74:77], v[216:219], v[162:165], v[74:77]
	v_mfma_f32_16x16x32_bf16 v[94:97], v[200:203], v[170:173], v[94:97]
	v_mfma_f32_16x16x32_bf16 v[66:69], v[216:219], v[170:173], v[66:69]
	v_mfma_f32_16x16x32_bf16 v[114:117], v[212:215], v[150:153], v[114:117]
	v_mfma_f32_16x16x32_bf16 v[86:89], v[220:223], v[150:153], v[86:89]
	v_mfma_f32_16x16x32_bf16 v[110:113], v[212:215], v[158:161], v[110:113]
	v_mfma_f32_16x16x32_bf16 v[82:85], v[220:223], v[158:161], v[82:85]
	v_mfma_f32_16x16x32_bf16 v[98:101], v[212:215], v[166:169], v[98:101]
	v_mfma_f32_16x16x32_bf16 v[74:77], v[220:223], v[166:169], v[74:77]
	v_mfma_f32_16x16x32_bf16 v[94:97], v[212:215], v[174:177], v[94:97]
	v_mfma_f32_16x16x32_bf16 v[66:69], v[220:223], v[174:177], v[66:69]
	s_add_i32 s74, s74, 2
	s_add_u32 s0, s0, 0x100
	s_addc_u32 s1, s1, 0
	s_add_u32 s72, s72, 0x100
	s_addc_u32 s73, s73, 0
	s_cmp_gt_u32 s74, 13
	s_barrier
	s_cbranch_scc1 .Lpeel_p8_exit
.LBB0_1090:
	ds_read_b128 v[130:133], v181
	ds_read_b128 v[134:137], v181 offset:1024
	ds_read_b128 v[138:141], v181 offset:2048
	ds_read_b128 v[142:145], v181 offset:3072
	s_add_u32 s2, s0, 0xfffc0080
	s_addc_u32 s3, s1, -1
	s_cmp_eq_u32 s74, 12
	s_cselect_b32 s45, s33, s3
	s_cselect_b32 s44, s39, s2
	s_cselect_b32 s3, s37, s73
	s_cselect_b32 s2, s71, s72
	s_add_i32 m0, s52, 0xc000
	ds_read_b128 v[146:149], v183
	ds_read_b128 v[150:153], v183 offset:1024
	ds_read_b128 v[154:157], v183 offset:2048
	ds_read_b128 v[158:161], v183 offset:3072
	ds_read_b128 v[162:165], v183 offset:4096
	ds_read_b128 v[166:169], v183 offset:5120
	ds_read_b128 v[170:173], v183 offset:6144
	global_load_lds_dwordx4 v192, s[0:1]
	s_add_i32 m0, s52, 0xe000
	ds_read_b128 v[174:177], v183 offset:7168
	global_load_lds_dwordx4 v194, s[0:1]
	s_waitcnt lgkmcnt(8)
	s_barrier
	s_waitcnt lgkmcnt(0)
	v_mfma_f32_16x16x32_bf16 v[62:65], v[130:133], v[146:149], v[62:65]
	v_mfma_f32_16x16x32_bf16 v[30:33], v[138:141], v[146:149], v[30:33]
	v_mfma_f32_16x16x32_bf16 v[54:57], v[130:133], v[154:157], v[54:57]
	v_mfma_f32_16x16x32_bf16 v[22:25], v[138:141], v[154:157], v[22:25]
	v_mfma_f32_16x16x32_bf16 v[46:49], v[130:133], v[162:165], v[46:49]
	v_mfma_f32_16x16x32_bf16 v[14:17], v[138:141], v[162:165], v[14:17]
	v_mfma_f32_16x16x32_bf16 v[38:41], v[130:133], v[170:173], v[38:41]
	v_mfma_f32_16x16x32_bf16 v[6:9], v[138:141], v[170:173], v[6:9]
	v_mfma_f32_16x16x32_bf16 v[62:65], v[134:137], v[150:153], v[62:65]
	v_mfma_f32_16x16x32_bf16 v[30:33], v[142:145], v[150:153], v[30:33]
	v_mfma_f32_16x16x32_bf16 v[54:57], v[134:137], v[158:161], v[54:57]
	v_mfma_f32_16x16x32_bf16 v[22:25], v[142:145], v[158:161], v[22:25]
	v_mfma_f32_16x16x32_bf16 v[46:49], v[134:137], v[166:169], v[46:49]
	v_mfma_f32_16x16x32_bf16 v[14:17], v[142:145], v[166:169], v[14:17]
	v_mfma_f32_16x16x32_bf16 v[38:41], v[134:137], v[174:177], v[38:41]
	v_mfma_f32_16x16x32_bf16 v[6:9], v[142:145], v[174:177], v[6:9]
	s_barrier
	s_add_i32 s75, s66, s51
	s_add_u32 s98, s2, 0x80
	s_addc_u32 s99, s3, 0
	s_mov_b32 m0, s75
	ds_read_b128 v[200:203], v206
	ds_read_b128 v[212:215], v206 offset:1024
	ds_read_b128 v[216:219], v206 offset:2048
	global_load_lds_dwordx4 v186, s[2:3]
	s_add_i32 m0, s75, 0x2000
	ds_read_b128 v[220:223], v206 offset:3072
	global_load_lds_dwordx4 v190, s[2:3]
	s_barrier
	s_waitcnt lgkmcnt(0)
	v_mfma_f32_16x16x32_bf16 v[58:61], v[200:203], v[146:149], v[58:61]
	v_mfma_f32_16x16x32_bf16 v[26:29], v[216:219], v[146:149], v[26:29]
	v_mfma_f32_16x16x32_bf16 v[50:53], v[200:203], v[154:157], v[50:53]
	v_mfma_f32_16x16x32_bf16 v[18:21], v[216:219], v[154:157], v[18:21]
	v_mfma_f32_16x16x32_bf16 v[42:45], v[200:203], v[162:165], v[42:45]
	v_mfma_f32_16x16x32_bf16 v[10:13], v[216:219], v[162:165], v[10:13]
	v_mfma_f32_16x16x32_bf16 v[34:37], v[200:203], v[170:173], v[34:37]
	v_mfma_f32_16x16x32_bf16 v[2:5], v[216:219], v[170:173], v[2:5]
	v_mfma_f32_16x16x32_bf16 v[58:61], v[212:215], v[150:153], v[58:61]
	v_mfma_f32_16x16x32_bf16 v[26:29], v[220:223], v[150:153], v[26:29]
	v_mfma_f32_16x16x32_bf16 v[50:53], v[212:215], v[158:161], v[50:53]
	v_mfma_f32_16x16x32_bf16 v[18:21], v[220:223], v[158:161], v[18:21]
	v_mfma_f32_16x16x32_bf16 v[42:45], v[212:215], v[166:169], v[42:45]
	v_mfma_f32_16x16x32_bf16 v[10:13], v[220:223], v[166:169], v[10:13]
	v_mfma_f32_16x16x32_bf16 v[34:37], v[212:215], v[174:177], v[34:37]
	v_mfma_f32_16x16x32_bf16 v[2:5], v[220:223], v[174:177], v[2:5]
	s_mov_b32 m0, s52
	s_add_u32 s100, s44, 0x80
	s_addc_u32 s101, s45, 0
	s_barrier
	ds_read_b128 v[146:149], v183 offset:16384
	ds_read_b128 v[150:153], v183 offset:17408
	ds_read_b128 v[154:157], v183 offset:18432
	ds_read_b128 v[158:161], v183 offset:19456
	ds_read_b128 v[162:165], v183 offset:20480
	ds_read_b128 v[166:169], v183 offset:21504
	ds_read_b128 v[170:173], v183 offset:22528
	global_load_lds_dwordx4 v184, s[44:45]
	s_mov_b32 m0, s53
	ds_read_b128 v[174:177], v183 offset:23552
	global_load_lds_dwordx4 v188, s[44:45]
	s_barrier
	s_waitcnt lgkmcnt(0)
	v_mfma_f32_16x16x32_bf16 v[126:129], v[130:133], v[146:149], v[126:129]
	v_mfma_f32_16x16x32_bf16 v[102:105], v[138:141], v[146:149], v[102:105]
	v_mfma_f32_16x16x32_bf16 v[122:125], v[130:133], v[154:157], v[122:125]
	v_mfma_f32_16x16x32_bf16 v[90:93], v[138:141], v[154:157], v[90:93]
	v_mfma_f32_16x16x32_bf16 v[118:121], v[130:133], v[162:165], v[118:121]
	v_mfma_f32_16x16x32_bf16 v[78:81], v[138:141], v[162:165], v[78:81]
	v_mfma_f32_16x16x32_bf16 v[106:109], v[130:133], v[170:173], v[106:109]
	v_mfma_f32_16x16x32_bf16 v[70:73], v[138:141], v[170:173], v[70:73]
	v_mfma_f32_16x16x32_bf16 v[126:129], v[134:137], v[150:153], v[126:129]
	v_mfma_f32_16x16x32_bf16 v[102:105], v[142:145], v[150:153], v[102:105]
	v_mfma_f32_16x16x32_bf16 v[122:125], v[134:137], v[158:161], v[122:125]
	v_mfma_f32_16x16x32_bf16 v[90:93], v[142:145], v[158:161], v[90:93]
	v_mfma_f32_16x16x32_bf16 v[118:121], v[134:137], v[166:169], v[118:121]
	v_mfma_f32_16x16x32_bf16 v[78:81], v[142:145], v[166:169], v[78:81]
	v_mfma_f32_16x16x32_bf16 v[106:109], v[134:137], v[174:177], v[106:109]
	v_mfma_f32_16x16x32_bf16 v[70:73], v[142:145], v[174:177], v[70:73]
	s_barrier
	s_add_u32 s76, s2, 0x40000
	s_addc_u32 s77, s3, 0
	s_add_i32 s75, s67, s51
	s_mov_b32 m0, s75
	s_nop 0
	global_load_lds_dwordx4 v186, s[76:77]
	s_add_i32 m0, s75, 0x2000
	s_nop 0
	global_load_lds_dwordx4 v190, s[76:77]
	s_waitcnt vmcnt(6)
	s_barrier
	v_mfma_f32_16x16x32_bf16 v[114:117], v[200:203], v[146:149], v[114:117]
	v_mfma_f32_16x16x32_bf16 v[86:89], v[216:219], v[146:149], v[86:89]
	v_mfma_f32_16x16x32_bf16 v[110:113], v[200:203], v[154:157], v[110:113]
	v_mfma_f32_16x16x32_bf16 v[82:85], v[216:219], v[154:157], v[82:85]
	v_mfma_f32_16x16x32_bf16 v[98:101], v[200:203], v[162:165], v[98:101]
	v_mfma_f32_16x16x32_bf16 v[74:77], v[216:219], v[162:165], v[74:77]
	v_mfma_f32_16x16x32_bf16 v[94:97], v[200:203], v[170:173], v[94:97]
	v_mfma_f32_16x16x32_bf16 v[66:69], v[216:219], v[170:173], v[66:69]
	v_mfma_f32_16x16x32_bf16 v[114:117], v[212:215], v[150:153], v[114:117]
	v_mfma_f32_16x16x32_bf16 v[86:89], v[220:223], v[150:153], v[86:89]
	v_mfma_f32_16x16x32_bf16 v[110:113], v[212:215], v[158:161], v[110:113]
	v_mfma_f32_16x16x32_bf16 v[82:85], v[220:223], v[158:161], v[82:85]
	v_mfma_f32_16x16x32_bf16 v[98:101], v[212:215], v[166:169], v[98:101]
	v_mfma_f32_16x16x32_bf16 v[74:77], v[220:223], v[166:169], v[74:77]
	v_mfma_f32_16x16x32_bf16 v[94:97], v[212:215], v[174:177], v[94:97]
	v_mfma_f32_16x16x32_bf16 v[66:69], v[220:223], v[174:177], v[66:69]
	s_add_i32 s75, 0, 0x18000
	v_add_u32_e32 v142, s75, v1
	s_barrier
	ds_read_b128 v[130:133], v142
	ds_read_b128 v[134:137], v142 offset:1024
	ds_read_b128 v[138:141], v142 offset:2048
	ds_read_b128 v[142:145], v142 offset:3072
	s_add_u32 s44, s44, 0x40000
	s_addc_u32 s45, s45, 0
	s_mov_b32 m0, s54
	ds_read_b128 v[146:149], v183 offset:32768
	ds_read_b128 v[150:153], v183 offset:33792
	ds_read_b128 v[154:157], v183 offset:34816
	ds_read_b128 v[158:161], v183 offset:35840
	ds_read_b128 v[162:165], v183 offset:36864
	ds_read_b128 v[166:169], v183 offset:37888
	ds_read_b128 v[170:173], v183 offset:38912
	global_load_lds_dwordx4 v184, s[44:45]
	s_mov_b32 m0, s55
	ds_read_b128 v[174:177], v183 offset:39936
	global_load_lds_dwordx4 v188, s[44:45]
	s_waitcnt lgkmcnt(8)
	s_barrier
	s_waitcnt lgkmcnt(0)
	v_mfma_f32_16x16x32_bf16 v[62:65], v[130:133], v[146:149], v[62:65]
	v_mfma_f32_16x16x32_bf16 v[30:33], v[138:141], v[146:149], v[30:33]
	v_mfma_f32_16x16x32_bf16 v[54:57], v[130:133], v[154:157], v[54:57]
	v_mfma_f32_16x16x32_bf16 v[22:25], v[138:141], v[154:157], v[22:25]
	v_mfma_f32_16x16x32_bf16 v[46:49], v[130:133], v[162:165], v[46:49]
	v_mfma_f32_16x16x32_bf16 v[14:17], v[138:141], v[162:165], v[14:17]
	v_mfma_f32_16x16x32_bf16 v[38:41], v[130:133], v[170:173], v[38:41]
	v_mfma_f32_16x16x32_bf16 v[6:9], v[138:141], v[170:173], v[6:9]
	v_mfma_f32_16x16x32_bf16 v[62:65], v[134:137], v[150:153], v[62:65]
	v_mfma_f32_16x16x32_bf16 v[30:33], v[142:145], v[150:153], v[30:33]
	v_mfma_f32_16x16x32_bf16 v[54:57], v[134:137], v[158:161], v[54:57]
	v_mfma_f32_16x16x32_bf16 v[22:25], v[142:145], v[158:161], v[22:25]
	v_mfma_f32_16x16x32_bf16 v[46:49], v[134:137], v[166:169], v[46:49]
	v_mfma_f32_16x16x32_bf16 v[14:17], v[142:145], v[166:169], v[14:17]
	v_mfma_f32_16x16x32_bf16 v[38:41], v[134:137], v[174:177], v[38:41]
	v_mfma_f32_16x16x32_bf16 v[6:9], v[142:145], v[174:177], v[6:9]
	s_barrier
	s_add_i32 s44, 0, 0x1c000
	s_add_i32 s45, s75, s51
	v_add_u32_e32 v207, s44, v1
	s_mov_b32 m0, s45
	ds_read_b128 v[200:203], v207
	ds_read_b128 v[212:215], v207 offset:1024
	ds_read_b128 v[216:219], v207 offset:2048
	global_load_lds_dwordx4 v186, s[98:99]
	s_add_i32 m0, s45, 0x2000
	ds_read_b128 v[220:223], v207 offset:3072
	global_load_lds_dwordx4 v190, s[98:99]
	s_barrier
	s_waitcnt lgkmcnt(0)
	v_mfma_f32_16x16x32_bf16 v[58:61], v[200:203], v[146:149], v[58:61]
	v_mfma_f32_16x16x32_bf16 v[26:29], v[216:219], v[146:149], v[26:29]
	v_mfma_f32_16x16x32_bf16 v[50:53], v[200:203], v[154:157], v[50:53]
	v_mfma_f32_16x16x32_bf16 v[18:21], v[216:219], v[154:157], v[18:21]
	v_mfma_f32_16x16x32_bf16 v[42:45], v[200:203], v[162:165], v[42:45]
	v_mfma_f32_16x16x32_bf16 v[10:13], v[216:219], v[162:165], v[10:13]
	v_mfma_f32_16x16x32_bf16 v[34:37], v[200:203], v[170:173], v[34:37]
	v_mfma_f32_16x16x32_bf16 v[2:5], v[216:219], v[170:173], v[2:5]
	v_mfma_f32_16x16x32_bf16 v[58:61], v[212:215], v[150:153], v[58:61]
	v_mfma_f32_16x16x32_bf16 v[26:29], v[220:223], v[150:153], v[26:29]
	v_mfma_f32_16x16x32_bf16 v[50:53], v[212:215], v[158:161], v[50:53]
	v_mfma_f32_16x16x32_bf16 v[18:21], v[220:223], v[158:161], v[18:21]
	v_mfma_f32_16x16x32_bf16 v[42:45], v[212:215], v[166:169], v[42:45]
	v_mfma_f32_16x16x32_bf16 v[10:13], v[220:223], v[166:169], v[10:13]
	v_mfma_f32_16x16x32_bf16 v[34:37], v[212:215], v[174:177], v[34:37]
	v_mfma_f32_16x16x32_bf16 v[2:5], v[220:223], v[174:177], v[2:5]
	s_mov_b32 m0, s59
	s_barrier
	ds_read_b128 v[146:149], v183 offset:49152
	ds_read_b128 v[150:153], v183 offset:50176
	ds_read_b128 v[154:157], v183 offset:51200
	ds_read_b128 v[158:161], v183 offset:52224
	ds_read_b128 v[162:165], v183 offset:53248
	ds_read_b128 v[166:169], v183 offset:54272
	ds_read_b128 v[170:173], v183 offset:55296
	global_load_lds_dwordx4 v184, s[100:101]
	s_mov_b32 m0, s60
	ds_read_b128 v[174:177], v183 offset:56320
	global_load_lds_dwordx4 v188, s[100:101]
	s_barrier
	s_waitcnt lgkmcnt(0)
	v_mfma_f32_16x16x32_bf16 v[126:129], v[130:133], v[146:149], v[126:129]
	v_mfma_f32_16x16x32_bf16 v[102:105], v[138:141], v[146:149], v[102:105]
	v_mfma_f32_16x16x32_bf16 v[122:125], v[130:133], v[154:157], v[122:125]
	v_mfma_f32_16x16x32_bf16 v[90:93], v[138:141], v[154:157], v[90:93]
	v_mfma_f32_16x16x32_bf16 v[118:121], v[130:133], v[162:165], v[118:121]
	v_mfma_f32_16x16x32_bf16 v[78:81], v[138:141], v[162:165], v[78:81]
	v_mfma_f32_16x16x32_bf16 v[106:109], v[130:133], v[170:173], v[106:109]
	v_mfma_f32_16x16x32_bf16 v[70:73], v[138:141], v[170:173], v[70:73]
	v_mfma_f32_16x16x32_bf16 v[126:129], v[134:137], v[150:153], v[126:129]
	v_mfma_f32_16x16x32_bf16 v[102:105], v[142:145], v[150:153], v[102:105]
	v_mfma_f32_16x16x32_bf16 v[122:125], v[134:137], v[158:161], v[122:125]
	v_mfma_f32_16x16x32_bf16 v[90:93], v[142:145], v[158:161], v[90:93]
	v_mfma_f32_16x16x32_bf16 v[118:121], v[134:137], v[166:169], v[118:121]
	v_mfma_f32_16x16x32_bf16 v[78:81], v[142:145], v[166:169], v[78:81]
	v_mfma_f32_16x16x32_bf16 v[106:109], v[134:137], v[174:177], v[106:109]
	v_mfma_f32_16x16x32_bf16 v[70:73], v[142:145], v[174:177], v[70:73]
	s_barrier
	s_add_u32 s2, s2, 0x40080
	s_addc_u32 s3, s3, 0
	s_add_i32 s44, s44, s51
	s_mov_b32 m0, s44
	s_nop 0
	global_load_lds_dwordx4 v186, s[2:3]
	s_add_i32 m0, s44, 0x2000
	s_nop 0
	global_load_lds_dwordx4 v190, s[2:3]
	s_waitcnt vmcnt(6)
	s_barrier
	v_mfma_f32_16x16x32_bf16 v[114:117], v[200:203], v[146:149], v[114:117]
	v_mfma_f32_16x16x32_bf16 v[86:89], v[216:219], v[146:149], v[86:89]
	v_mfma_f32_16x16x32_bf16 v[110:113], v[200:203], v[154:157], v[110:113]
	v_mfma_f32_16x16x32_bf16 v[82:85], v[216:219], v[154:157], v[82:85]
	v_mfma_f32_16x16x32_bf16 v[98:101], v[200:203], v[162:165], v[98:101]
	v_mfma_f32_16x16x32_bf16 v[74:77], v[216:219], v[162:165], v[74:77]
	v_mfma_f32_16x16x32_bf16 v[94:97], v[200:203], v[170:173], v[94:97]
	v_mfma_f32_16x16x32_bf16 v[66:69], v[216:219], v[170:173], v[66:69]
	v_mfma_f32_16x16x32_bf16 v[114:117], v[212:215], v[150:153], v[114:117]
	v_mfma_f32_16x16x32_bf16 v[86:89], v[220:223], v[150:153], v[86:89]
	v_mfma_f32_16x16x32_bf16 v[110:113], v[212:215], v[158:161], v[110:113]
	v_mfma_f32_16x16x32_bf16 v[82:85], v[220:223], v[158:161], v[82:85]
	v_mfma_f32_16x16x32_bf16 v[98:101], v[212:215], v[166:169], v[98:101]
	v_mfma_f32_16x16x32_bf16 v[74:77], v[220:223], v[166:169], v[74:77]
	v_mfma_f32_16x16x32_bf16 v[94:97], v[212:215], v[174:177], v[94:97]
	v_mfma_f32_16x16x32_bf16 v[66:69], v[220:223], v[174:177], v[66:69]
	s_add_i32 s74, s74, 2
	s_add_u32 s0, s0, 0x100
	s_addc_u32 s1, s1, 0
	s_add_u32 s72, s72, 0x100
	s_addc_u32 s73, s73, 0
	s_cmp_gt_u32 s74, 13
	s_barrier
	s_cbranch_scc0 .LBB0_1090

.Lpeel_p10:
	ds_read_b128 v[152:155], v149
	ds_read_b128 v[156:159], v149 offset:1024
	ds_read_b128 v[160:163], v149 offset:2048
	ds_read_b128 v[164:167], v149 offset:3072
	s_add_u32 s18, s16, 0xfff50080
	s_addc_u32 s19, s17, -1
	s_cmp_eq_u32 s54, 40
	s_cselect_b32 s21, s3, s19
	s_cselect_b32 s20, s2, s18
	s_cselect_b32 s19, s5, s53
	s_cselect_b32 s18, s4, s52
	s_add_i32 m0, s30, 0xc000
	ds_read_b128 v[168:171], v150
	ds_read_b128 v[172:175], v150 offset:1024
	ds_read_b128 v[180:183], v150 offset:2048
	ds_read_b128 v[184:187], v150 offset:3072
	ds_read_b128 v[188:191], v150 offset:4096
	ds_read_b128 v[192:195], v150 offset:5120
	ds_read_b128 v[196:199], v150 offset:6144
	global_load_lds_dwordx4 v138, s[16:17]
	s_add_i32 m0, s30, 0xe000
	ds_read_b128 v[200:203], v150 offset:7168
	global_load_lds_dwordx4 v140, s[16:17]
	s_waitcnt lgkmcnt(8)
	s_barrier
	s_waitcnt lgkmcnt(0)
	v_mfma_f32_16x16x32_bf16 v[126:129], v[152:155], v[168:171], 0
	v_mfma_f32_16x16x32_bf16 v[122:125], v[160:163], v[168:171], 0
	v_mfma_f32_16x16x32_bf16 v[114:117], v[152:155], v[180:183], 0
	v_mfma_f32_16x16x32_bf16 v[106:109], v[160:163], v[180:183], 0
	v_mfma_f32_16x16x32_bf16 v[98:101], v[152:155], v[188:191], 0
	v_mfma_f32_16x16x32_bf16 v[90:93], v[160:163], v[188:191], 0
	v_mfma_f32_16x16x32_bf16 v[82:85], v[152:155], v[196:199], 0
	v_mfma_f32_16x16x32_bf16 v[74:77], v[160:163], v[196:199], 0
	v_mfma_f32_16x16x32_bf16 v[126:129], v[156:159], v[172:175], v[126:129]
	v_mfma_f32_16x16x32_bf16 v[122:125], v[164:167], v[172:175], v[122:125]
	v_mfma_f32_16x16x32_bf16 v[114:117], v[156:159], v[184:187], v[114:117]
	v_mfma_f32_16x16x32_bf16 v[106:109], v[164:167], v[184:187], v[106:109]
	v_mfma_f32_16x16x32_bf16 v[98:101], v[156:159], v[192:195], v[98:101]
	v_mfma_f32_16x16x32_bf16 v[90:93], v[164:167], v[192:195], v[90:93]
	v_mfma_f32_16x16x32_bf16 v[82:85], v[156:159], v[200:203], v[82:85]
	v_mfma_f32_16x16x32_bf16 v[74:77], v[164:167], v[200:203], v[74:77]
	s_barrier
	s_add_i32 s55, s41, s27
	s_add_u32 s98, s18, 0x80
	s_addc_u32 s99, s19, 0
	s_mov_b32 m0, s55
	ds_read_b128 v[206:209], v151
	ds_read_b128 v[212:215], v151 offset:1024
	ds_read_b128 v[216:219], v151 offset:2048
	global_load_lds_dwordx4 v134, s[18:19]
	s_add_i32 m0, s55, 0x2000
	ds_read_b128 v[220:223], v151 offset:3072
	global_load_lds_dwordx4 v136, s[18:19]
	s_barrier
	s_waitcnt lgkmcnt(0)
	v_mfma_f32_16x16x32_bf16 v[118:121], v[206:209], v[168:171], 0
	v_mfma_f32_16x16x32_bf16 v[110:113], v[216:219], v[168:171], 0
	v_mfma_f32_16x16x32_bf16 v[102:105], v[206:209], v[180:183], 0
	v_mfma_f32_16x16x32_bf16 v[94:97], v[216:219], v[180:183], 0
	v_mfma_f32_16x16x32_bf16 v[86:89], v[206:209], v[188:191], 0
	v_mfma_f32_16x16x32_bf16 v[78:81], v[216:219], v[188:191], 0
	v_mfma_f32_16x16x32_bf16 v[70:73], v[206:209], v[196:199], 0
	v_mfma_f32_16x16x32_bf16 v[66:69], v[216:219], v[196:199], 0
	v_mfma_f32_16x16x32_bf16 v[118:121], v[212:215], v[172:175], v[118:121]
	v_mfma_f32_16x16x32_bf16 v[110:113], v[220:223], v[172:175], v[110:113]
	v_mfma_f32_16x16x32_bf16 v[102:105], v[212:215], v[184:187], v[102:105]
	v_mfma_f32_16x16x32_bf16 v[94:97], v[220:223], v[184:187], v[94:97]
	v_mfma_f32_16x16x32_bf16 v[86:89], v[212:215], v[192:195], v[86:89]
	v_mfma_f32_16x16x32_bf16 v[78:81], v[220:223], v[192:195], v[78:81]
	v_mfma_f32_16x16x32_bf16 v[70:73], v[212:215], v[200:203], v[70:73]
	v_mfma_f32_16x16x32_bf16 v[66:69], v[220:223], v[200:203], v[66:69]
	s_mov_b32 m0, s30
	s_add_u32 s100, s20, 0x80
	s_addc_u32 s101, s21, 0
	s_barrier
	ds_read_b128 v[168:171], v150 offset:16384
	ds_read_b128 v[172:175], v150 offset:17408
	ds_read_b128 v[180:183], v150 offset:18432
	ds_read_b128 v[184:187], v150 offset:19456
	ds_read_b128 v[188:191], v150 offset:20480
	ds_read_b128 v[192:195], v150 offset:21504
	ds_read_b128 v[196:199], v150 offset:22528
	global_load_lds_dwordx4 v130, s[20:21]
	s_mov_b32 m0, s31
	ds_read_b128 v[200:203], v150 offset:23552
	global_load_lds_dwordx4 v132, s[20:21]
	s_barrier
	s_waitcnt lgkmcnt(0)
	v_mfma_f32_16x16x32_bf16 v[62:65], v[152:155], v[168:171], 0
	v_mfma_f32_16x16x32_bf16 v[58:61], v[160:163], v[168:171], 0
	v_mfma_f32_16x16x32_bf16 v[50:53], v[152:155], v[180:183], 0
	v_mfma_f32_16x16x32_bf16 v[42:45], v[160:163], v[180:183], 0
	v_mfma_f32_16x16x32_bf16 v[34:37], v[152:155], v[188:191], 0
	v_mfma_f32_16x16x32_bf16 v[26:29], v[160:163], v[188:191], 0
	v_mfma_f32_16x16x32_bf16 v[18:21], v[152:155], v[196:199], 0
	v_mfma_f32_16x16x32_bf16 v[10:13], v[160:163], v[196:199], 0
	v_mfma_f32_16x16x32_bf16 v[62:65], v[156:159], v[172:175], v[62:65]
	v_mfma_f32_16x16x32_bf16 v[58:61], v[164:167], v[172:175], v[58:61]
	v_mfma_f32_16x16x32_bf16 v[50:53], v[156:159], v[184:187], v[50:53]
	v_mfma_f32_16x16x32_bf16 v[42:45], v[164:167], v[184:187], v[42:45]
	v_mfma_f32_16x16x32_bf16 v[34:37], v[156:159], v[192:195], v[34:37]
	v_mfma_f32_16x16x32_bf16 v[26:29], v[164:167], v[192:195], v[26:29]
	v_mfma_f32_16x16x32_bf16 v[18:21], v[156:159], v[200:203], v[18:21]
	v_mfma_f32_16x16x32_bf16 v[10:13], v[164:167], v[200:203], v[10:13]
	s_barrier
	s_add_u32 s56, s18, 0xb0000
	s_addc_u32 s57, s19, 0
	s_add_i32 s55, s42, s27
	s_mov_b32 m0, s55
	s_nop 0
	global_load_lds_dwordx4 v134, s[56:57]
	s_add_i32 m0, s55, 0x2000
	s_nop 0
	global_load_lds_dwordx4 v136, s[56:57]
	s_waitcnt vmcnt(6)
	s_barrier
	v_mfma_f32_16x16x32_bf16 v[54:57], v[206:209], v[168:171], 0
	v_mfma_f32_16x16x32_bf16 v[46:49], v[216:219], v[168:171], 0
	v_mfma_f32_16x16x32_bf16 v[38:41], v[206:209], v[180:183], 0
	v_mfma_f32_16x16x32_bf16 v[30:33], v[216:219], v[180:183], 0
	v_mfma_f32_16x16x32_bf16 v[22:25], v[206:209], v[188:191], 0
	v_mfma_f32_16x16x32_bf16 v[14:17], v[216:219], v[188:191], 0
	v_mfma_f32_16x16x32_bf16 v[6:9], v[206:209], v[196:199], 0
	v_mfma_f32_16x16x32_bf16 v[2:5], v[216:219], v[196:199], 0
	v_mfma_f32_16x16x32_bf16 v[54:57], v[212:215], v[172:175], v[54:57]
	v_mfma_f32_16x16x32_bf16 v[46:49], v[220:223], v[172:175], v[46:49]
	v_mfma_f32_16x16x32_bf16 v[38:41], v[212:215], v[184:187], v[38:41]
	v_mfma_f32_16x16x32_bf16 v[30:33], v[220:223], v[184:187], v[30:33]
	v_mfma_f32_16x16x32_bf16 v[22:25], v[212:215], v[192:195], v[22:25]
	v_mfma_f32_16x16x32_bf16 v[14:17], v[220:223], v[192:195], v[14:17]
	v_mfma_f32_16x16x32_bf16 v[6:9], v[212:215], v[200:203], v[6:9]
	v_mfma_f32_16x16x32_bf16 v[2:5], v[220:223], v[200:203], v[2:5]
	s_add_i32 s55, 0, 0x18000
	v_add_u32_e32 v164, s55, v148
	s_barrier
	ds_read_b128 v[152:155], v164
	ds_read_b128 v[156:159], v164 offset:1024
	ds_read_b128 v[160:163], v164 offset:2048
	ds_read_b128 v[164:167], v164 offset:3072
	s_add_u32 s20, s20, 0xb0000
	s_addc_u32 s21, s21, 0
	s_mov_b32 m0, s33
	ds_read_b128 v[168:171], v150 offset:32768
	ds_read_b128 v[172:175], v150 offset:33792
	ds_read_b128 v[180:183], v150 offset:34816
	ds_read_b128 v[184:187], v150 offset:35840
	ds_read_b128 v[188:191], v150 offset:36864
	ds_read_b128 v[192:195], v150 offset:37888
	ds_read_b128 v[196:199], v150 offset:38912
	global_load_lds_dwordx4 v130, s[20:21]
	s_mov_b32 m0, s34
	ds_read_b128 v[200:203], v150 offset:39936
	global_load_lds_dwordx4 v132, s[20:21]
	s_waitcnt lgkmcnt(8)
	s_barrier
	s_waitcnt lgkmcnt(0)
	v_mfma_f32_16x16x32_bf16 v[126:129], v[152:155], v[168:171], v[126:129]
	v_mfma_f32_16x16x32_bf16 v[122:125], v[160:163], v[168:171], v[122:125]
	v_mfma_f32_16x16x32_bf16 v[114:117], v[152:155], v[180:183], v[114:117]
	v_mfma_f32_16x16x32_bf16 v[106:109], v[160:163], v[180:183], v[106:109]
	v_mfma_f32_16x16x32_bf16 v[98:101], v[152:155], v[188:191], v[98:101]
	v_mfma_f32_16x16x32_bf16 v[90:93], v[160:163], v[188:191], v[90:93]
	v_mfma_f32_16x16x32_bf16 v[82:85], v[152:155], v[196:199], v[82:85]
	v_mfma_f32_16x16x32_bf16 v[74:77], v[160:163], v[196:199], v[74:77]
	v_mfma_f32_16x16x32_bf16 v[126:129], v[156:159], v[172:175], v[126:129]
	v_mfma_f32_16x16x32_bf16 v[122:125], v[164:167], v[172:175], v[122:125]
	v_mfma_f32_16x16x32_bf16 v[114:117], v[156:159], v[184:187], v[114:117]
	v_mfma_f32_16x16x32_bf16 v[106:109], v[164:167], v[184:187], v[106:109]
	v_mfma_f32_16x16x32_bf16 v[98:101], v[156:159], v[192:195], v[98:101]
	v_mfma_f32_16x16x32_bf16 v[90:93], v[164:167], v[192:195], v[90:93]
	v_mfma_f32_16x16x32_bf16 v[82:85], v[156:159], v[200:203], v[82:85]
	v_mfma_f32_16x16x32_bf16 v[74:77], v[164:167], v[200:203], v[74:77]
	s_barrier
	s_add_i32 s20, 0, 0x1c000
	s_add_i32 s21, s55, s27
	v_add_u32_e32 v179, s20, v148
	s_mov_b32 m0, s21
	ds_read_b128 v[206:209], v179
	ds_read_b128 v[212:215], v179 offset:1024
	ds_read_b128 v[216:219], v179 offset:2048
	global_load_lds_dwordx4 v134, s[98:99]
	s_add_i32 m0, s21, 0x2000
	ds_read_b128 v[220:223], v179 offset:3072
	global_load_lds_dwordx4 v136, s[98:99]
	s_barrier
	s_waitcnt lgkmcnt(0)
	v_mfma_f32_16x16x32_bf16 v[118:121], v[206:209], v[168:171], v[118:121]
	v_mfma_f32_16x16x32_bf16 v[110:113], v[216:219], v[168:171], v[110:113]
	v_mfma_f32_16x16x32_bf16 v[102:105], v[206:209], v[180:183], v[102:105]
	v_mfma_f32_16x16x32_bf16 v[94:97], v[216:219], v[180:183], v[94:97]
	v_mfma_f32_16x16x32_bf16 v[86:89], v[206:209], v[188:191], v[86:89]
	v_mfma_f32_16x16x32_bf16 v[78:81], v[216:219], v[188:191], v[78:81]
	v_mfma_f32_16x16x32_bf16 v[70:73], v[206:209], v[196:199], v[70:73]
	v_mfma_f32_16x16x32_bf16 v[66:69], v[216:219], v[196:199], v[66:69]
	v_mfma_f32_16x16x32_bf16 v[118:121], v[212:215], v[172:175], v[118:121]
	v_mfma_f32_16x16x32_bf16 v[110:113], v[220:223], v[172:175], v[110:113]
	v_mfma_f32_16x16x32_bf16 v[102:105], v[212:215], v[184:187], v[102:105]
	v_mfma_f32_16x16x32_bf16 v[94:97], v[220:223], v[184:187], v[94:97]
	v_mfma_f32_16x16x32_bf16 v[86:89], v[212:215], v[192:195], v[86:89]
	v_mfma_f32_16x16x32_bf16 v[78:81], v[220:223], v[192:195], v[78:81]
	v_mfma_f32_16x16x32_bf16 v[70:73], v[212:215], v[200:203], v[70:73]
	v_mfma_f32_16x16x32_bf16 v[66:69], v[220:223], v[200:203], v[66:69]
	s_mov_b32 m0, s37
	s_barrier
	ds_read_b128 v[168:171], v150 offset:49152
	ds_read_b128 v[172:175], v150 offset:50176
	ds_read_b128 v[180:183], v150 offset:51200
	ds_read_b128 v[184:187], v150 offset:52224
	ds_read_b128 v[188:191], v150 offset:53248
	ds_read_b128 v[192:195], v150 offset:54272
	ds_read_b128 v[196:199], v150 offset:55296
	global_load_lds_dwordx4 v130, s[100:101]
	s_mov_b32 m0, s38
	ds_read_b128 v[200:203], v150 offset:56320
	global_load_lds_dwordx4 v132, s[100:101]
	s_barrier
	s_waitcnt lgkmcnt(0)
	v_mfma_f32_16x16x32_bf16 v[62:65], v[152:155], v[168:171], v[62:65]
	v_mfma_f32_16x16x32_bf16 v[58:61], v[160:163], v[168:171], v[58:61]
	v_mfma_f32_16x16x32_bf16 v[50:53], v[152:155], v[180:183], v[50:53]
	v_mfma_f32_16x16x32_bf16 v[42:45], v[160:163], v[180:183], v[42:45]
	v_mfma_f32_16x16x32_bf16 v[34:37], v[152:155], v[188:191], v[34:37]
	v_mfma_f32_16x16x32_bf16 v[26:29], v[160:163], v[188:191], v[26:29]
	v_mfma_f32_16x16x32_bf16 v[18:21], v[152:155], v[196:199], v[18:21]
	v_mfma_f32_16x16x32_bf16 v[10:13], v[160:163], v[196:199], v[10:13]
	v_mfma_f32_16x16x32_bf16 v[62:65], v[156:159], v[172:175], v[62:65]
	v_mfma_f32_16x16x32_bf16 v[58:61], v[164:167], v[172:175], v[58:61]
	v_mfma_f32_16x16x32_bf16 v[50:53], v[156:159], v[184:187], v[50:53]
	v_mfma_f32_16x16x32_bf16 v[42:45], v[164:167], v[184:187], v[42:45]
	v_mfma_f32_16x16x32_bf16 v[34:37], v[156:159], v[192:195], v[34:37]
	v_mfma_f32_16x16x32_bf16 v[26:29], v[164:167], v[192:195], v[26:29]
	v_mfma_f32_16x16x32_bf16 v[18:21], v[156:159], v[200:203], v[18:21]
	v_mfma_f32_16x16x32_bf16 v[10:13], v[164:167], v[200:203], v[10:13]
	s_barrier
	s_add_u32 s18, s18, 0xb0080
	s_addc_u32 s19, s19, 0
	s_add_i32 s20, s20, s27
	s_mov_b32 m0, s20
	s_nop 0
	global_load_lds_dwordx4 v134, s[18:19]
	s_add_i32 m0, s20, 0x2000
	s_nop 0
	global_load_lds_dwordx4 v136, s[18:19]
	s_waitcnt vmcnt(6)
	s_barrier
	v_mfma_f32_16x16x32_bf16 v[54:57], v[206:209], v[168:171], v[54:57]
	v_mfma_f32_16x16x32_bf16 v[46:49], v[216:219], v[168:171], v[46:49]
	v_mfma_f32_16x16x32_bf16 v[38:41], v[206:209], v[180:183], v[38:41]
	v_mfma_f32_16x16x32_bf16 v[30:33], v[216:219], v[180:183], v[30:33]
	v_mfma_f32_16x16x32_bf16 v[22:25], v[206:209], v[188:191], v[22:25]
	v_mfma_f32_16x16x32_bf16 v[14:17], v[216:219], v[188:191], v[14:17]
	v_mfma_f32_16x16x32_bf16 v[6:9], v[206:209], v[196:199], v[6:9]
	v_mfma_f32_16x16x32_bf16 v[2:5], v[216:219], v[196:199], v[2:5]
	v_mfma_f32_16x16x32_bf16 v[54:57], v[212:215], v[172:175], v[54:57]
	v_mfma_f32_16x16x32_bf16 v[46:49], v[220:223], v[172:175], v[46:49]
	v_mfma_f32_16x16x32_bf16 v[38:41], v[212:215], v[184:187], v[38:41]
	v_mfma_f32_16x16x32_bf16 v[30:33], v[220:223], v[184:187], v[30:33]
	v_mfma_f32_16x16x32_bf16 v[22:25], v[212:215], v[192:195], v[22:25]
	v_mfma_f32_16x16x32_bf16 v[14:17], v[220:223], v[192:195], v[14:17]
	v_mfma_f32_16x16x32_bf16 v[6:9], v[212:215], v[200:203], v[6:9]
	v_mfma_f32_16x16x32_bf16 v[2:5], v[220:223], v[200:203], v[2:5]
	s_add_i32 s54, s54, 2
	s_add_u32 s16, s16, 0x100
	s_addc_u32 s17, s17, 0
	s_add_u32 s52, s52, 0x100
	s_addc_u32 s53, s53, 0
	s_cmp_gt_u32 s54, 41
	s_barrier
	s_cbranch_scc1 .Lpeel_p10_exit
.LBB0_1197:
	ds_read_b128 v[152:155], v149
	ds_read_b128 v[156:159], v149 offset:1024
	ds_read_b128 v[160:163], v149 offset:2048
	ds_read_b128 v[164:167], v149 offset:3072
	s_add_u32 s18, s16, 0xfff50080
	s_addc_u32 s19, s17, -1
	s_cmp_eq_u32 s54, 40
	s_cselect_b32 s21, s3, s19
	s_cselect_b32 s20, s2, s18
	s_cselect_b32 s19, s5, s53
	s_cselect_b32 s18, s4, s52
	s_add_i32 m0, s30, 0xc000
	ds_read_b128 v[168:171], v150
	ds_read_b128 v[172:175], v150 offset:1024
	ds_read_b128 v[180:183], v150 offset:2048
	ds_read_b128 v[184:187], v150 offset:3072
	ds_read_b128 v[188:191], v150 offset:4096
	ds_read_b128 v[192:195], v150 offset:5120
	ds_read_b128 v[196:199], v150 offset:6144
	global_load_lds_dwordx4 v138, s[16:17]
	s_add_i32 m0, s30, 0xe000
	ds_read_b128 v[200:203], v150 offset:7168
	global_load_lds_dwordx4 v140, s[16:17]
	s_waitcnt lgkmcnt(8)
	s_barrier
	s_waitcnt lgkmcnt(0)
	v_mfma_f32_16x16x32_bf16 v[126:129], v[152:155], v[168:171], v[126:129]
	v_mfma_f32_16x16x32_bf16 v[122:125], v[160:163], v[168:171], v[122:125]
	v_mfma_f32_16x16x32_bf16 v[114:117], v[152:155], v[180:183], v[114:117]
	v_mfma_f32_16x16x32_bf16 v[106:109], v[160:163], v[180:183], v[106:109]
	v_mfma_f32_16x16x32_bf16 v[98:101], v[152:155], v[188:191], v[98:101]
	v_mfma_f32_16x16x32_bf16 v[90:93], v[160:163], v[188:191], v[90:93]
	v_mfma_f32_16x16x32_bf16 v[82:85], v[152:155], v[196:199], v[82:85]
	v_mfma_f32_16x16x32_bf16 v[74:77], v[160:163], v[196:199], v[74:77]
	v_mfma_f32_16x16x32_bf16 v[126:129], v[156:159], v[172:175], v[126:129]
	v_mfma_f32_16x16x32_bf16 v[122:125], v[164:167], v[172:175], v[122:125]
	v_mfma_f32_16x16x32_bf16 v[114:117], v[156:159], v[184:187], v[114:117]
	v_mfma_f32_16x16x32_bf16 v[106:109], v[164:167], v[184:187], v[106:109]
	v_mfma_f32_16x16x32_bf16 v[98:101], v[156:159], v[192:195], v[98:101]
	v_mfma_f32_16x16x32_bf16 v[90:93], v[164:167], v[192:195], v[90:93]
	v_mfma_f32_16x16x32_bf16 v[82:85], v[156:159], v[200:203], v[82:85]
	v_mfma_f32_16x16x32_bf16 v[74:77], v[164:167], v[200:203], v[74:77]
	s_barrier
	s_add_i32 s55, s41, s27
	s_add_u32 s98, s18, 0x80
	s_addc_u32 s99, s19, 0
	s_mov_b32 m0, s55
	ds_read_b128 v[206:209], v151
	ds_read_b128 v[212:215], v151 offset:1024
	ds_read_b128 v[216:219], v151 offset:2048
	global_load_lds_dwordx4 v134, s[18:19]
	s_add_i32 m0, s55, 0x2000
	ds_read_b128 v[220:223], v151 offset:3072
	global_load_lds_dwordx4 v136, s[18:19]
	s_barrier
	s_waitcnt lgkmcnt(0)
	v_mfma_f32_16x16x32_bf16 v[118:121], v[206:209], v[168:171], v[118:121]
	v_mfma_f32_16x16x32_bf16 v[110:113], v[216:219], v[168:171], v[110:113]
	v_mfma_f32_16x16x32_bf16 v[102:105], v[206:209], v[180:183], v[102:105]
	v_mfma_f32_16x16x32_bf16 v[94:97], v[216:219], v[180:183], v[94:97]
	v_mfma_f32_16x16x32_bf16 v[86:89], v[206:209], v[188:191], v[86:89]
	v_mfma_f32_16x16x32_bf16 v[78:81], v[216:219], v[188:191], v[78:81]
	v_mfma_f32_16x16x32_bf16 v[70:73], v[206:209], v[196:199], v[70:73]
	v_mfma_f32_16x16x32_bf16 v[66:69], v[216:219], v[196:199], v[66:69]
	v_mfma_f32_16x16x32_bf16 v[118:121], v[212:215], v[172:175], v[118:121]
	v_mfma_f32_16x16x32_bf16 v[110:113], v[220:223], v[172:175], v[110:113]
	v_mfma_f32_16x16x32_bf16 v[102:105], v[212:215], v[184:187], v[102:105]
	v_mfma_f32_16x16x32_bf16 v[94:97], v[220:223], v[184:187], v[94:97]
	v_mfma_f32_16x16x32_bf16 v[86:89], v[212:215], v[192:195], v[86:89]
	v_mfma_f32_16x16x32_bf16 v[78:81], v[220:223], v[192:195], v[78:81]
	v_mfma_f32_16x16x32_bf16 v[70:73], v[212:215], v[200:203], v[70:73]
	v_mfma_f32_16x16x32_bf16 v[66:69], v[220:223], v[200:203], v[66:69]
	s_mov_b32 m0, s30
	s_add_u32 s100, s20, 0x80
	s_addc_u32 s101, s21, 0
	s_barrier
	ds_read_b128 v[168:171], v150 offset:16384
	ds_read_b128 v[172:175], v150 offset:17408
	ds_read_b128 v[180:183], v150 offset:18432
	ds_read_b128 v[184:187], v150 offset:19456
	ds_read_b128 v[188:191], v150 offset:20480
	ds_read_b128 v[192:195], v150 offset:21504
	ds_read_b128 v[196:199], v150 offset:22528
	global_load_lds_dwordx4 v130, s[20:21]
	s_mov_b32 m0, s31
	ds_read_b128 v[200:203], v150 offset:23552
	global_load_lds_dwordx4 v132, s[20:21]
	s_barrier
	s_waitcnt lgkmcnt(0)
	v_mfma_f32_16x16x32_bf16 v[62:65], v[152:155], v[168:171], v[62:65]
	v_mfma_f32_16x16x32_bf16 v[58:61], v[160:163], v[168:171], v[58:61]
	v_mfma_f32_16x16x32_bf16 v[50:53], v[152:155], v[180:183], v[50:53]
	v_mfma_f32_16x16x32_bf16 v[42:45], v[160:163], v[180:183], v[42:45]
	v_mfma_f32_16x16x32_bf16 v[34:37], v[152:155], v[188:191], v[34:37]
	v_mfma_f32_16x16x32_bf16 v[26:29], v[160:163], v[188:191], v[26:29]
	v_mfma_f32_16x16x32_bf16 v[18:21], v[152:155], v[196:199], v[18:21]
	v_mfma_f32_16x16x32_bf16 v[10:13], v[160:163], v[196:199], v[10:13]
	v_mfma_f32_16x16x32_bf16 v[62:65], v[156:159], v[172:175], v[62:65]
	v_mfma_f32_16x16x32_bf16 v[58:61], v[164:167], v[172:175], v[58:61]
	v_mfma_f32_16x16x32_bf16 v[50:53], v[156:159], v[184:187], v[50:53]
	v_mfma_f32_16x16x32_bf16 v[42:45], v[164:167], v[184:187], v[42:45]
	v_mfma_f32_16x16x32_bf16 v[34:37], v[156:159], v[192:195], v[34:37]
	v_mfma_f32_16x16x32_bf16 v[26:29], v[164:167], v[192:195], v[26:29]
	v_mfma_f32_16x16x32_bf16 v[18:21], v[156:159], v[200:203], v[18:21]
	v_mfma_f32_16x16x32_bf16 v[10:13], v[164:167], v[200:203], v[10:13]
	s_barrier
	s_add_u32 s56, s18, 0xb0000
	s_addc_u32 s57, s19, 0
	s_add_i32 s55, s42, s27
	s_mov_b32 m0, s55
	s_nop 0
	global_load_lds_dwordx4 v134, s[56:57]
	s_add_i32 m0, s55, 0x2000
	s_nop 0
	global_load_lds_dwordx4 v136, s[56:57]
	s_waitcnt vmcnt(6)
	s_barrier
	v_mfma_f32_16x16x32_bf16 v[54:57], v[206:209], v[168:171], v[54:57]
	v_mfma_f32_16x16x32_bf16 v[46:49], v[216:219], v[168:171], v[46:49]
	v_mfma_f32_16x16x32_bf16 v[38:41], v[206:209], v[180:183], v[38:41]
	v_mfma_f32_16x16x32_bf16 v[30:33], v[216:219], v[180:183], v[30:33]
	v_mfma_f32_16x16x32_bf16 v[22:25], v[206:209], v[188:191], v[22:25]
	v_mfma_f32_16x16x32_bf16 v[14:17], v[216:219], v[188:191], v[14:17]
	v_mfma_f32_16x16x32_bf16 v[6:9], v[206:209], v[196:199], v[6:9]
	v_mfma_f32_16x16x32_bf16 v[2:5], v[216:219], v[196:199], v[2:5]
	v_mfma_f32_16x16x32_bf16 v[54:57], v[212:215], v[172:175], v[54:57]
	v_mfma_f32_16x16x32_bf16 v[46:49], v[220:223], v[172:175], v[46:49]
	v_mfma_f32_16x16x32_bf16 v[38:41], v[212:215], v[184:187], v[38:41]
	v_mfma_f32_16x16x32_bf16 v[30:33], v[220:223], v[184:187], v[30:33]
	v_mfma_f32_16x16x32_bf16 v[22:25], v[212:215], v[192:195], v[22:25]
	v_mfma_f32_16x16x32_bf16 v[14:17], v[220:223], v[192:195], v[14:17]
	v_mfma_f32_16x16x32_bf16 v[6:9], v[212:215], v[200:203], v[6:9]
	v_mfma_f32_16x16x32_bf16 v[2:5], v[220:223], v[200:203], v[2:5]
	s_add_i32 s55, 0, 0x18000
	v_add_u32_e32 v164, s55, v148
	s_barrier
	ds_read_b128 v[152:155], v164
	ds_read_b128 v[156:159], v164 offset:1024
	ds_read_b128 v[160:163], v164 offset:2048
	ds_read_b128 v[164:167], v164 offset:3072
	s_add_u32 s20, s20, 0xb0000
	s_addc_u32 s21, s21, 0
	s_mov_b32 m0, s33
	ds_read_b128 v[168:171], v150 offset:32768
	ds_read_b128 v[172:175], v150 offset:33792
	ds_read_b128 v[180:183], v150 offset:34816
	ds_read_b128 v[184:187], v150 offset:35840
	ds_read_b128 v[188:191], v150 offset:36864
	ds_read_b128 v[192:195], v150 offset:37888
	ds_read_b128 v[196:199], v150 offset:38912
	global_load_lds_dwordx4 v130, s[20:21]
	s_mov_b32 m0, s34
	ds_read_b128 v[200:203], v150 offset:39936
	global_load_lds_dwordx4 v132, s[20:21]
	s_waitcnt lgkmcnt(8)
	s_barrier
	s_waitcnt lgkmcnt(0)
	v_mfma_f32_16x16x32_bf16 v[126:129], v[152:155], v[168:171], v[126:129]
	v_mfma_f32_16x16x32_bf16 v[122:125], v[160:163], v[168:171], v[122:125]
	v_mfma_f32_16x16x32_bf16 v[114:117], v[152:155], v[180:183], v[114:117]
	v_mfma_f32_16x16x32_bf16 v[106:109], v[160:163], v[180:183], v[106:109]
	v_mfma_f32_16x16x32_bf16 v[98:101], v[152:155], v[188:191], v[98:101]
	v_mfma_f32_16x16x32_bf16 v[90:93], v[160:163], v[188:191], v[90:93]
	v_mfma_f32_16x16x32_bf16 v[82:85], v[152:155], v[196:199], v[82:85]
	v_mfma_f32_16x16x32_bf16 v[74:77], v[160:163], v[196:199], v[74:77]
	v_mfma_f32_16x16x32_bf16 v[126:129], v[156:159], v[172:175], v[126:129]
	v_mfma_f32_16x16x32_bf16 v[122:125], v[164:167], v[172:175], v[122:125]
	v_mfma_f32_16x16x32_bf16 v[114:117], v[156:159], v[184:187], v[114:117]
	v_mfma_f32_16x16x32_bf16 v[106:109], v[164:167], v[184:187], v[106:109]
	v_mfma_f32_16x16x32_bf16 v[98:101], v[156:159], v[192:195], v[98:101]
	v_mfma_f32_16x16x32_bf16 v[90:93], v[164:167], v[192:195], v[90:93]
	v_mfma_f32_16x16x32_bf16 v[82:85], v[156:159], v[200:203], v[82:85]
	v_mfma_f32_16x16x32_bf16 v[74:77], v[164:167], v[200:203], v[74:77]
	s_barrier
	s_add_i32 s20, 0, 0x1c000
	s_add_i32 s21, s55, s27
	v_add_u32_e32 v179, s20, v148
	s_mov_b32 m0, s21
	ds_read_b128 v[206:209], v179
	ds_read_b128 v[212:215], v179 offset:1024
	ds_read_b128 v[216:219], v179 offset:2048
	global_load_lds_dwordx4 v134, s[98:99]
	s_add_i32 m0, s21, 0x2000
	ds_read_b128 v[220:223], v179 offset:3072
	global_load_lds_dwordx4 v136, s[98:99]
	s_barrier
	s_waitcnt lgkmcnt(0)
	v_mfma_f32_16x16x32_bf16 v[118:121], v[206:209], v[168:171], v[118:121]
	v_mfma_f32_16x16x32_bf16 v[110:113], v[216:219], v[168:171], v[110:113]
	v_mfma_f32_16x16x32_bf16 v[102:105], v[206:209], v[180:183], v[102:105]
	v_mfma_f32_16x16x32_bf16 v[94:97], v[216:219], v[180:183], v[94:97]
	v_mfma_f32_16x16x32_bf16 v[86:89], v[206:209], v[188:191], v[86:89]
	v_mfma_f32_16x16x32_bf16 v[78:81], v[216:219], v[188:191], v[78:81]
	v_mfma_f32_16x16x32_bf16 v[70:73], v[206:209], v[196:199], v[70:73]
	v_mfma_f32_16x16x32_bf16 v[66:69], v[216:219], v[196:199], v[66:69]
	v_mfma_f32_16x16x32_bf16 v[118:121], v[212:215], v[172:175], v[118:121]
	v_mfma_f32_16x16x32_bf16 v[110:113], v[220:223], v[172:175], v[110:113]
	v_mfma_f32_16x16x32_bf16 v[102:105], v[212:215], v[184:187], v[102:105]
	v_mfma_f32_16x16x32_bf16 v[94:97], v[220:223], v[184:187], v[94:97]
	v_mfma_f32_16x16x32_bf16 v[86:89], v[212:215], v[192:195], v[86:89]
	v_mfma_f32_16x16x32_bf16 v[78:81], v[220:223], v[192:195], v[78:81]
	v_mfma_f32_16x16x32_bf16 v[70:73], v[212:215], v[200:203], v[70:73]
	v_mfma_f32_16x16x32_bf16 v[66:69], v[220:223], v[200:203], v[66:69]
	s_mov_b32 m0, s37
	s_barrier
	ds_read_b128 v[168:171], v150 offset:49152
	ds_read_b128 v[172:175], v150 offset:50176
	ds_read_b128 v[180:183], v150 offset:51200
	ds_read_b128 v[184:187], v150 offset:52224
	ds_read_b128 v[188:191], v150 offset:53248
	ds_read_b128 v[192:195], v150 offset:54272
	ds_read_b128 v[196:199], v150 offset:55296
	global_load_lds_dwordx4 v130, s[100:101]
	s_mov_b32 m0, s38
	ds_read_b128 v[200:203], v150 offset:56320
	global_load_lds_dwordx4 v132, s[100:101]
	s_barrier
	s_waitcnt lgkmcnt(0)
	v_mfma_f32_16x16x32_bf16 v[62:65], v[152:155], v[168:171], v[62:65]
	v_mfma_f32_16x16x32_bf16 v[58:61], v[160:163], v[168:171], v[58:61]
	v_mfma_f32_16x16x32_bf16 v[50:53], v[152:155], v[180:183], v[50:53]
	v_mfma_f32_16x16x32_bf16 v[42:45], v[160:163], v[180:183], v[42:45]
	v_mfma_f32_16x16x32_bf16 v[34:37], v[152:155], v[188:191], v[34:37]
	v_mfma_f32_16x16x32_bf16 v[26:29], v[160:163], v[188:191], v[26:29]
	v_mfma_f32_16x16x32_bf16 v[18:21], v[152:155], v[196:199], v[18:21]
	v_mfma_f32_16x16x32_bf16 v[10:13], v[160:163], v[196:199], v[10:13]
	v_mfma_f32_16x16x32_bf16 v[62:65], v[156:159], v[172:175], v[62:65]
	v_mfma_f32_16x16x32_bf16 v[58:61], v[164:167], v[172:175], v[58:61]
	v_mfma_f32_16x16x32_bf16 v[50:53], v[156:159], v[184:187], v[50:53]
	v_mfma_f32_16x16x32_bf16 v[42:45], v[164:167], v[184:187], v[42:45]
	v_mfma_f32_16x16x32_bf16 v[34:37], v[156:159], v[192:195], v[34:37]
	v_mfma_f32_16x16x32_bf16 v[26:29], v[164:167], v[192:195], v[26:29]
	v_mfma_f32_16x16x32_bf16 v[18:21], v[156:159], v[200:203], v[18:21]
	v_mfma_f32_16x16x32_bf16 v[10:13], v[164:167], v[200:203], v[10:13]
	s_barrier
	s_add_u32 s18, s18, 0xb0080
	s_addc_u32 s19, s19, 0
	s_add_i32 s20, s20, s27
	s_mov_b32 m0, s20
	s_nop 0
	global_load_lds_dwordx4 v134, s[18:19]
	s_add_i32 m0, s20, 0x2000
	s_nop 0
	global_load_lds_dwordx4 v136, s[18:19]
	s_waitcnt vmcnt(6)
	s_barrier
	v_mfma_f32_16x16x32_bf16 v[54:57], v[206:209], v[168:171], v[54:57]
	v_mfma_f32_16x16x32_bf16 v[46:49], v[216:219], v[168:171], v[46:49]
	v_mfma_f32_16x16x32_bf16 v[38:41], v[206:209], v[180:183], v[38:41]
	v_mfma_f32_16x16x32_bf16 v[30:33], v[216:219], v[180:183], v[30:33]
	v_mfma_f32_16x16x32_bf16 v[22:25], v[206:209], v[188:191], v[22:25]
	v_mfma_f32_16x16x32_bf16 v[14:17], v[216:219], v[188:191], v[14:17]
	v_mfma_f32_16x16x32_bf16 v[6:9], v[206:209], v[196:199], v[6:9]
	v_mfma_f32_16x16x32_bf16 v[2:5], v[216:219], v[196:199], v[2:5]
	v_mfma_f32_16x16x32_bf16 v[54:57], v[212:215], v[172:175], v[54:57]
	v_mfma_f32_16x16x32_bf16 v[46:49], v[220:223], v[172:175], v[46:49]
	v_mfma_f32_16x16x32_bf16 v[38:41], v[212:215], v[184:187], v[38:41]
	v_mfma_f32_16x16x32_bf16 v[30:33], v[220:223], v[184:187], v[30:33]
	v_mfma_f32_16x16x32_bf16 v[22:25], v[212:215], v[192:195], v[22:25]
	v_mfma_f32_16x16x32_bf16 v[14:17], v[220:223], v[192:195], v[14:17]
	v_mfma_f32_16x16x32_bf16 v[6:9], v[212:215], v[200:203], v[6:9]
	v_mfma_f32_16x16x32_bf16 v[2:5], v[220:223], v[200:203], v[2:5]
	s_add_i32 s54, s54, 2
	s_add_u32 s16, s16, 0x100
	s_addc_u32 s17, s17, 0
	s_add_u32 s52, s52, 0x100
	s_addc_u32 s53, s53, 0
	s_cmp_gt_u32 s54, 41
	s_barrier
	s_cbranch_scc0 .LBB0_1197
